# attention loop rebalanced: K-fragment reads + V k-step 0/1 prefetch + first exp group moved into the QK phase, PV phase starts with MFMAs; sc1 on GEMM epilogue dwordx4 stores
# baseline (speedup 1.0000x reference)
.Lattn_cb_ok:
	s_waitcnt lgkmcnt(0)
	v_mfma_f32_32x32x16_bf16 v[64:79], v[132:135], v[108:111], v[168:183]
	s_add_i32 s54, s65, 0xffff8000
	s_and_b32 s54, s54, 0x18000
	v_mfma_f32_32x32x16_bf16 v[80:95], v[116:119], v[108:111], v[168:183]
	s_branch .Lattn_qk_rest

.Lattn_qk_rest:
	v_add_u32_e32 v116, s54, v214
	v_add_u32_e32 v216, v116, v157
	v_add_u32_e32 v218, v116, v208
	v_add_u32_e32 v217, v116, v193
	v_add_u32_e32 v219, v116, v209
	v_mfma_f32_32x32x16_bf16 v[64:79], v[136:139], v[104:107], v[64:79]
	v_mfma_f32_32x32x16_bf16 v[80:95], v[120:123], v[104:107], v[80:95]
	v_mfma_f32_32x32x16_bf16 v[64:79], v[140:143], v[100:103], v[64:79]
	v_mfma_f32_32x32x16_bf16 v[80:95], v[124:127], v[100:103], v[80:95]
	v_mfma_f32_32x32x16_bf16 v[80:95], v[112:115], v[96:99], v[80:95]
	ds_read_b128 v[242:245], v216 offset:16384
	ds_read_b128 v[246:249], v216 offset:20480
	ds_read_b128 v[250:253], v216 offset:24576
	ds_read_b128 v[200:203], v216 offset:28672
	ds_read_b128 v[220:223], v217 offset:16384
	ds_read_b128 v[224:227], v217 offset:20480
	ds_read_b128 v[234:237], v217 offset:24576
	ds_read_b128 v[238:241], v217 offset:28672
	v_mfma_f32_32x32x16_bf16 v[64:79], v[128:131], v[96:99], v[64:79]
	s_nop 11
	v_max_f32_e32 v128, v65, v65
	v_max_f32_e32 v129, v64, v64
	v_max_f32_e32 v128, v129, v128
	v_max3_f32 v129, v66, v67, v81
	v_max3_f32 v128, v128, v80, v82
	v_max3_f32 v128, v128, v83, v68
	v_max3_f32 v129, v129, v70, v71
	v_max3_f32 v128, v128, v69, v84
	v_max3_f32 v129, v129, v86, v87
	v_max3_f32 v128, v128, v85, v72
	v_max3_f32 v129, v129, v74, v75
	v_max3_f32 v128, v128, v73, v88
	v_max3_f32 v129, v129, v90, v91
	v_max3_f32 v128, v128, v89, v76
	v_max3_f32 v129, v129, v78, v79
	v_max3_f32 v128, v128, v77, v92
	v_max3_f32 v129, v129, v94, v95
	v_max3_f32 v128, v128, v93, v129
	v_cmp_lt_f32_e32 vcc, s88, v128
	s_cbranch_vccz .LBB0_276
	ds_bpermute_b32 v129, v210, v128
	s_waitcnt lgkmcnt(0)
	v_max_f32_e32 v129, v129, v129
	v_max_f32_e32 v128, v128, v129
	v_cmp_lt_f32_e32 vcc, s88, v128
	s_nop 0
	s_mov_b32 s98, 0
	s_nop 0
	v_cndmask_b32_e32 v128, 0, v128, vcc
	v_exp_f32_e64 v130, -v128
	v_pk_add_f32 v[64:65], v[64:65], v[128:129] op_sel_hi:[1,0] neg_lo:[0,1] neg_hi:[0,1]
	v_pk_add_f32 v[80:81], v[80:81], v[128:129] op_sel_hi:[1,0] neg_lo:[0,1] neg_hi:[0,1]
	v_pk_add_f32 v[66:67], v[66:67], v[128:129] op_sel_hi:[1,0] neg_lo:[0,1] neg_hi:[0,1]
	v_pk_mul_f32 v[46:47], v[46:47], v[130:131] op_sel_hi:[1,0]
	v_pk_mul_f32 v[44:45], v[44:45], v[130:131] op_sel_hi:[1,0]
	v_pk_mul_f32 v[42:43], v[42:43], v[130:131] op_sel_hi:[1,0]
	v_pk_mul_f32 v[40:41], v[40:41], v[130:131] op_sel_hi:[1,0]
	v_pk_mul_f32 v[38:39], v[38:39], v[130:131] op_sel_hi:[1,0]
	v_pk_mul_f32 v[36:37], v[36:37], v[130:131] op_sel_hi:[1,0]
	v_pk_mul_f32 v[34:35], v[34:35], v[130:131] op_sel_hi:[1,0]
	v_pk_mul_f32 v[32:33], v[32:33], v[130:131] op_sel_hi:[1,0]
	v_pk_mul_f32 v[62:63], v[62:63], v[130:131] op_sel_hi:[1,0]
	v_pk_mul_f32 v[60:61], v[60:61], v[130:131] op_sel_hi:[1,0]
	v_pk_mul_f32 v[58:59], v[58:59], v[130:131] op_sel_hi:[1,0]
	v_pk_mul_f32 v[56:57], v[56:57], v[130:131] op_sel_hi:[1,0]
	v_pk_mul_f32 v[54:55], v[54:55], v[130:131] op_sel_hi:[1,0]
	v_pk_mul_f32 v[52:53], v[52:53], v[130:131] op_sel_hi:[1,0]
	v_pk_mul_f32 v[50:51], v[50:51], v[130:131] op_sel_hi:[1,0]
	v_pk_mul_f32 v[48:49], v[48:49], v[130:131] op_sel_hi:[1,0]
	v_pk_mul_f32 v[30:31], v[30:31], v[130:131] op_sel_hi:[1,0]
	v_pk_mul_f32 v[28:29], v[28:29], v[130:131] op_sel_hi:[1,0]
	v_pk_mul_f32 v[26:27], v[26:27], v[130:131] op_sel_hi:[1,0]
	v_pk_mul_f32 v[24:25], v[24:25], v[130:131] op_sel_hi:[1,0]
	v_pk_mul_f32 v[22:23], v[22:23], v[130:131] op_sel_hi:[1,0]
	v_pk_mul_f32 v[20:21], v[20:21], v[130:131] op_sel_hi:[1,0]
	v_pk_mul_f32 v[18:19], v[18:19], v[130:131] op_sel_hi:[1,0]
	v_pk_mul_f32 v[16:17], v[16:17], v[130:131] op_sel_hi:[1,0]
	v_pk_mul_f32 v[14:15], v[14:15], v[130:131] op_sel_hi:[1,0]
	v_pk_mul_f32 v[12:13], v[12:13], v[130:131] op_sel_hi:[1,0]
	v_pk_mul_f32 v[10:11], v[10:11], v[130:131] op_sel_hi:[1,0]
	v_pk_mul_f32 v[8:9], v[8:9], v[130:131] op_sel_hi:[1,0]
	v_pk_mul_f32 v[6:7], v[6:7], v[130:131] op_sel_hi:[1,0]
	v_pk_mul_f32 v[4:5], v[4:5], v[130:131] op_sel_hi:[1,0]
	v_pk_mul_f32 v[2:3], v[2:3], v[130:131] op_sel_hi:[1,0]
	v_pk_mul_f32 v[0:1], v[0:1], v[130:131] op_sel_hi:[1,0]
	v_mov_b32_e32 v131, v128
	v_pk_add_f32 v[82:83], v[82:83], v[128:129] op_sel_hi:[1,0] neg_lo:[0,1] neg_hi:[0,1]
	v_pk_add_f32 v[68:69], v[68:69], v[128:129] op_sel_hi:[1,0] neg_lo:[0,1] neg_hi:[0,1]
	v_pk_add_f32 v[84:85], v[84:85], v[128:129] op_sel_hi:[1,0] neg_lo:[0,1] neg_hi:[0,1]
	v_pk_add_f32 v[70:71], v[70:71], v[128:129] op_sel_hi:[1,0] neg_lo:[0,1] neg_hi:[0,1]
	v_pk_add_f32 v[86:87], v[86:87], v[128:129] op_sel_hi:[1,0] neg_lo:[0,1] neg_hi:[0,1]
	v_pk_add_f32 v[72:73], v[72:73], v[128:129] op_sel_hi:[1,0] neg_lo:[0,1] neg_hi:[0,1]
	v_pk_add_f32 v[88:89], v[88:89], v[128:129] op_sel_hi:[1,0] neg_lo:[0,1] neg_hi:[0,1]
	v_pk_add_f32 v[74:75], v[74:75], v[128:129] op_sel_hi:[1,0] neg_lo:[0,1] neg_hi:[0,1]
	v_pk_add_f32 v[90:91], v[90:91], v[128:129] op_sel_hi:[1,0] neg_lo:[0,1] neg_hi:[0,1]
	v_pk_add_f32 v[76:77], v[76:77], v[128:129] op_sel_hi:[1,0] neg_lo:[0,1] neg_hi:[0,1]
	v_pk_add_f32 v[92:93], v[92:93], v[128:129] op_sel_hi:[1,0] neg_lo:[0,1] neg_hi:[0,1]
	v_pk_add_f32 v[78:79], v[78:79], v[128:129] op_sel_hi:[1,0] neg_lo:[0,1] neg_hi:[0,1]
	v_pk_add_f32 v[94:95], v[94:95], v[128:129] op_sel_hi:[1,0] neg_lo:[0,1] neg_hi:[0,1]
	v_pk_add_f32 v[128:129], v[206:207], v[130:131]
	v_pk_mul_f32 v[206:207], v[206:207], v[130:131]
	s_nop 0
	v_mov_b32_e32 v207, v129
.LBB0_276:
	v_exp_f32_e32 v64, v64
	v_exp_f32_e32 v65, v65
	v_exp_f32_e32 v66, v66
	v_exp_f32_e32 v67, v67
	v_add_f32_e32 v184, v64, v65
	v_exp_f32_e32 v68, v68
	v_exp_f32_e32 v69, v69
	v_cvt_pk_bf16_f32 v64, v64, v65
	v_add_f32_e32 v185, v66, v67
	v_cvt_pk_bf16_f32 v65, v66, v67
	v_exp_f32_e32 v70, v70
	v_exp_f32_e32 v71, v71
	v_add_f32_e32 v186, v68, v69
	v_cvt_pk_bf16_f32 v66, v68, v69
	v_add_f32_e32 v184, v184, v185
	v_add_f32_e32 v187, v70, v71
	v_cvt_pk_bf16_f32 v67, v70, v71
	v_add_f32_e32 v186, v186, v187
	v_add_f32_e32 v184, v184, v186
	v_add_f32_e32 v206, v206, v184
	s_mov_b64 s[54:55], -1
	s_and_b64 vcc, exec, s[44:45]
	s_cbranch_vccnz .LBB0_282
	s_andn2_b64 vcc, exec, s[54:55]
	s_cbranch_vccz .LBB0_283

.LBB0_279:
	s_cmp_eq_u32 s54, 1
	s_cbranch_scc1 .Lattn_fullL
	s_cmp_eq_u32 s54, 29
	s_cbranch_scc1 .Lattn_fullL
	s_add_u32 s70, s70, 0x2000
	s_addc_u32 s71, s71, 0
	s_add_u32 s66, s66, 0x80
	s_addc_u32 s67, s67, 0
	s_branch .Lattn_ldsbL
.Lattn_fullL:
	s_cmp_lt_u32 s54, 29
	s_cselect_b32 s67, s13, s53
	s_cselect_b32 s55, 3, 0xffffffe3
	s_cselect_b32 s66, s22, s12
	s_or_b32 s70, s67, 8
	s_add_i32 s33, s55, s33
	s_ashr_i32 s71, s70, 31
	s_add_i32 s68, s33, 1
	s_lshl_b64 s[70:71], s[70:71], 18
	s_add_u32 s33, s8, s70
	s_addc_u32 s55, s9, s71
	s_ashr_i32 s69, s68, 31
	s_lshl_b64 s[70:71], s[68:69], 13
	s_add_u32 s70, s33, s70
	s_addc_u32 s71, s55, s71
	s_ashr_i32 s67, s66, 31
	s_lshl_b64 s[66:67], s[66:67], 12
	s_add_u32 s33, s10, s66
	s_addc_u32 s55, s11, s67
	s_lshl_b32 s66, s68, 6
	s_ashr_i32 s67, s66, 31
	s_lshl_b64 s[66:67], s[66:67], 1
	s_add_u32 s66, s33, s66
	s_addc_u32 s67, s55, s67
.Lattn_ldsbL:
	s_add_i32 s33, s65, 0x10000
	s_and_b32 s33, s33, 0x18000
	s_add_i32 s33, s57, s33
	v_lshlrev_b32_e32 v198, 1, v150
	v_mfma_f32_32x32x16_bf16 v[32:47], v[242:245], v[64:67], v[32:47]
	v_exp_f32_e32 v72, v72
	v_exp_f32_e32 v73, v73
	v_exp_f32_e32 v74, v74
	v_exp_f32_e32 v75, v75
	v_add_f32_e32 v184, v72, v73
	s_mov_b32 m0, s33
	s_nop 0
	global_load_lds_dwordx4 v188, s[70:71]
	v_mfma_f32_32x32x16_bf16 v[48:63], v[246:249], v[64:67], v[48:63]
	v_exp_f32_e32 v76, v76
	v_exp_f32_e32 v77, v77
	v_cvt_pk_bf16_f32 v68, v72, v73
	v_add_f32_e32 v185, v74, v75
	v_cvt_pk_bf16_f32 v69, v74, v75
	v_mfma_f32_32x32x16_bf16 v[16:31], v[250:253], v[64:67], v[16:31]
	v_exp_f32_e32 v78, v78
	v_exp_f32_e32 v79, v79
	v_add_f32_e32 v186, v76, v77
	v_cvt_pk_bf16_f32 v70, v76, v77
	v_add_f32_e32 v184, v184, v185
	s_add_u32 s100, s70, 0x40000
	s_addc_u32 s101, s71, 0
	s_add_i32 m0, s33, 0x2000
	s_nop 0
	global_load_lds_dwordx4 v188, s[100:101]
	v_mfma_f32_32x32x16_bf16 v[0:15], v[200:203], v[64:67], v[0:15]
	v_add_f32_e32 v187, v78, v79
	v_cvt_pk_bf16_f32 v71, v78, v79
	v_add_f32_e32 v186, v186, v187
	v_add_f32_e32 v184, v184, v186
	v_add_f32_e32 v206, v206, v184
	ds_read_b128 v[242:245], v218 offset:16384
	ds_read_b128 v[246:249], v218 offset:20480
	ds_read_b128 v[250:253], v218 offset:24576
	ds_read_b128 v[200:203], v218 offset:28672
	v_mfma_f32_32x32x16_bf16 v[32:47], v[220:223], v[68:71], v[32:47]
	v_exp_f32_e32 v80, v80
	v_exp_f32_e32 v81, v81
	v_exp_f32_e32 v82, v82
	v_exp_f32_e32 v83, v83
	v_add_f32_e32 v184, v80, v81
	s_add_i32 m0, s33, 0x4000
	s_nop 0
	global_load_lds_dwordx4 v198, s[66:67]
	v_mfma_f32_32x32x16_bf16 v[48:63], v[224:227], v[68:71], v[48:63]
	v_exp_f32_e32 v84, v84
	v_exp_f32_e32 v85, v85
	v_cvt_pk_bf16_f32 v72, v80, v81
	v_add_f32_e32 v185, v82, v83
	v_cvt_pk_bf16_f32 v73, v82, v83
	v_mfma_f32_32x32x16_bf16 v[16:31], v[234:237], v[68:71], v[16:31]
	v_exp_f32_e32 v86, v86
	v_exp_f32_e32 v87, v87
	v_add_f32_e32 v186, v84, v85
	v_cvt_pk_bf16_f32 v74, v84, v85
	v_add_f32_e32 v184, v184, v185
	s_add_u32 s100, s66, 0x40000
	s_addc_u32 s101, s67, 0
	s_add_i32 m0, s33, 0x6000
	s_nop 0
	global_load_lds_dwordx4 v198, s[100:101]
	v_mfma_f32_32x32x16_bf16 v[0:15], v[238:241], v[68:71], v[0:15]
	v_add_f32_e32 v187, v86, v87
	v_cvt_pk_bf16_f32 v75, v86, v87
	v_add_f32_e32 v186, v186, v187
	v_add_f32_e32 v184, v184, v186
	v_add_f32_e32 v206, v206, v184
	ds_read_b128 v[220:223], v219 offset:16384
	ds_read_b128 v[224:227], v219 offset:20480
	ds_read_b128 v[234:237], v219 offset:24576
	ds_read_b128 v[238:241], v219 offset:28672
	s_waitcnt lgkmcnt(4)
	v_mfma_f32_32x32x16_bf16 v[32:47], v[242:245], v[72:75], v[32:47]
	v_exp_f32_e32 v88, v88
	v_exp_f32_e32 v89, v89
	v_exp_f32_e32 v90, v90
	v_exp_f32_e32 v91, v91
	v_add_f32_e32 v184, v88, v89
	s_add_u32 s100, s70, 0x1000
	s_addc_u32 s101, s71, 0
	s_add_i32 m0, s33, 0x1000
	s_nop 0
	global_load_lds_dwordx4 v188, s[100:101]
	v_mfma_f32_32x32x16_bf16 v[48:63], v[246:249], v[72:75], v[48:63]
	v_exp_f32_e32 v92, v92
	v_exp_f32_e32 v93, v93
	v_cvt_pk_bf16_f32 v76, v88, v89
	v_add_f32_e32 v185, v90, v91
	v_cvt_pk_bf16_f32 v77, v90, v91
	v_mfma_f32_32x32x16_bf16 v[16:31], v[250:253], v[72:75], v[16:31]
	v_exp_f32_e32 v94, v94
	v_exp_f32_e32 v95, v95
	v_add_f32_e32 v186, v92, v93
	v_cvt_pk_bf16_f32 v78, v92, v93
	v_add_f32_e32 v184, v184, v185
	s_add_u32 s100, s70, 0x41000
	s_addc_u32 s101, s71, 0
	s_add_i32 m0, s33, 0x3000
	s_nop 0
	global_load_lds_dwordx4 v188, s[100:101]
	v_mfma_f32_32x32x16_bf16 v[0:15], v[200:203], v[72:75], v[0:15]
	v_add_f32_e32 v187, v94, v95
	v_cvt_pk_bf16_f32 v79, v94, v95
	v_add_f32_e32 v186, v186, v187
	v_add_f32_e32 v184, v184, v186
	v_add_f32_e32 v206, v206, v184
	s_waitcnt lgkmcnt(0)
	v_mfma_f32_32x32x16_bf16 v[32:47], v[220:223], v[76:79], v[32:47]
	s_add_u32 s100, s66, 0x20000
	s_addc_u32 s101, s67, 0
	s_add_i32 m0, s33, 0x5000
	s_nop 0
	global_load_lds_dwordx4 v198, s[100:101]
	v_mfma_f32_32x32x16_bf16 v[48:63], v[224:227], v[76:79], v[48:63]
	s_add_u32 s100, s66, 0x60000
	s_addc_u32 s101, s67, 0
	s_add_i32 m0, s33, 0x7000
	s_nop 0
	global_load_lds_dwordx4 v198, s[100:101]
	s_waitcnt lgkmcnt(0)
	s_barrier
	s_add_i32 s65, s65, 0x8000
	s_addk_i32 s23, 0x100
	s_add_i32 s36, s36, 64
	s_cmpk_eq_i32 s23, 0x1e00
	v_mfma_f32_32x32x16_bf16 v[16:31], v[234:237], v[76:79], v[16:31]
	v_mfma_f32_32x32x16_bf16 v[0:15], v[238:241], v[76:79], v[0:15]
	s_cbranch_scc1 .Lattn_exit
	s_branch .Lattn_tail
.LBB0_280:
	v_mfma_f32_32x32x16_bf16 v[32:47], v[242:245], v[64:67], v[32:47]
	v_exp_f32_e32 v72, v72
	v_exp_f32_e32 v73, v73
	v_exp_f32_e32 v74, v74
	v_exp_f32_e32 v75, v75
	v_add_f32_e32 v184, v72, v73
	v_mfma_f32_32x32x16_bf16 v[48:63], v[246:249], v[64:67], v[48:63]
	v_exp_f32_e32 v76, v76
	v_exp_f32_e32 v77, v77
	v_cvt_pk_bf16_f32 v68, v72, v73
	v_add_f32_e32 v185, v74, v75
	v_cvt_pk_bf16_f32 v69, v74, v75
	v_mfma_f32_32x32x16_bf16 v[16:31], v[250:253], v[64:67], v[16:31]
	v_exp_f32_e32 v78, v78
	v_exp_f32_e32 v79, v79
	v_add_f32_e32 v186, v76, v77
	v_cvt_pk_bf16_f32 v70, v76, v77
	v_add_f32_e32 v184, v184, v185
	v_mfma_f32_32x32x16_bf16 v[0:15], v[200:203], v[64:67], v[0:15]
	v_add_f32_e32 v187, v78, v79
	v_cvt_pk_bf16_f32 v71, v78, v79
	v_add_f32_e32 v186, v186, v187
	v_add_f32_e32 v184, v184, v186
	v_add_f32_e32 v206, v206, v184
	ds_read_b128 v[242:245], v218 offset:16384
	ds_read_b128 v[246:249], v218 offset:20480
	ds_read_b128 v[250:253], v218 offset:24576
	ds_read_b128 v[200:203], v218 offset:28672
	v_mfma_f32_32x32x16_bf16 v[32:47], v[220:223], v[68:71], v[32:47]
	v_exp_f32_e32 v80, v80
	v_exp_f32_e32 v81, v81
	v_exp_f32_e32 v82, v82
	v_exp_f32_e32 v83, v83
	v_add_f32_e32 v184, v80, v81
	v_mfma_f32_32x32x16_bf16 v[48:63], v[224:227], v[68:71], v[48:63]
	v_exp_f32_e32 v84, v84
	v_exp_f32_e32 v85, v85
	v_cvt_pk_bf16_f32 v72, v80, v81
	v_add_f32_e32 v185, v82, v83
	v_cvt_pk_bf16_f32 v73, v82, v83
	v_mfma_f32_32x32x16_bf16 v[16:31], v[234:237], v[68:71], v[16:31]
	v_exp_f32_e32 v86, v86
	v_exp_f32_e32 v87, v87
	v_add_f32_e32 v186, v84, v85
	v_cvt_pk_bf16_f32 v74, v84, v85
	v_add_f32_e32 v184, v184, v185
	v_mfma_f32_32x32x16_bf16 v[0:15], v[238:241], v[68:71], v[0:15]
	v_add_f32_e32 v187, v86, v87
	v_cvt_pk_bf16_f32 v75, v86, v87
	v_add_f32_e32 v186, v186, v187
	v_add_f32_e32 v184, v184, v186
	v_add_f32_e32 v206, v206, v184
	ds_read_b128 v[220:223], v219 offset:16384
	ds_read_b128 v[224:227], v219 offset:20480
	ds_read_b128 v[234:237], v219 offset:24576
	ds_read_b128 v[238:241], v219 offset:28672
	s_waitcnt lgkmcnt(4)
	v_mfma_f32_32x32x16_bf16 v[32:47], v[242:245], v[72:75], v[32:47]
	v_exp_f32_e32 v88, v88
	v_exp_f32_e32 v89, v89
	v_exp_f32_e32 v90, v90
	v_exp_f32_e32 v91, v91
	v_add_f32_e32 v184, v88, v89
	v_mfma_f32_32x32x16_bf16 v[48:63], v[246:249], v[72:75], v[48:63]
	v_exp_f32_e32 v92, v92
	v_exp_f32_e32 v93, v93
	v_cvt_pk_bf16_f32 v76, v88, v89
	v_add_f32_e32 v185, v90, v91
	v_cvt_pk_bf16_f32 v77, v90, v91
	v_mfma_f32_32x32x16_bf16 v[16:31], v[250:253], v[72:75], v[16:31]
	v_exp_f32_e32 v94, v94
	v_exp_f32_e32 v95, v95
	v_add_f32_e32 v186, v92, v93
	v_cvt_pk_bf16_f32 v78, v92, v93
	v_add_f32_e32 v184, v184, v185
	v_mfma_f32_32x32x16_bf16 v[0:15], v[200:203], v[72:75], v[0:15]
	v_add_f32_e32 v187, v94, v95
	v_cvt_pk_bf16_f32 v79, v94, v95
	v_add_f32_e32 v186, v186, v187
	v_add_f32_e32 v184, v184, v186
	v_add_f32_e32 v206, v206, v184
	s_waitcnt lgkmcnt(0)
	v_mfma_f32_32x32x16_bf16 v[32:47], v[220:223], v[76:79], v[32:47]
	v_mfma_f32_32x32x16_bf16 v[48:63], v[224:227], v[76:79], v[48:63]
	s_waitcnt lgkmcnt(0)
	s_barrier
	s_add_i32 s65, s65, 0x8000
	s_addk_i32 s23, 0x100
	s_add_i32 s36, s36, 64
	s_cmpk_eq_i32 s23, 0x1e00
	v_mfma_f32_32x32x16_bf16 v[16:31], v[234:237], v[76:79], v[16:31]
	v_mfma_f32_32x32x16_bf16 v[0:15], v[238:241], v[76:79], v[0:15]
	s_cbranch_scc1 .Lattn_exit
.Lattn_tail:
	s_add_i32 s100, s65, 0xffff8000
	s_and_b32 s100, s100, 0x18000
	v_add_u32_e32 v194, s100, v149
	v_add_u32_e32 v195, v194, v157
	v_add_u32_e32 v196, v194, v193
	v_add_u32_e32 v197, v194, v208
	v_add_u32_e32 v194, v194, v209
	ds_read_b128 v[132:135], v195
	ds_read_b128 v[116:119], v195 offset:4096
	ds_read_b128 v[136:139], v196
	ds_read_b128 v[120:123], v196 offset:4096
	ds_read_b128 v[140:143], v197
	ds_read_b128 v[124:127], v197 offset:4096
	ds_read_b128 v[128:131], v194
	ds_read_b128 v[112:115], v194 offset:4096
	s_mov_b32 s33, s54
	s_setprio 0
	s_cmp_gt_u32 s36, 0xfffffeec
	s_mov_b64 s[54:55], -1
	s_cbranch_scc1 .LBB0_271
	s_branch .LBB0_272
.Lattn_exit:
	s_add_i32 s100, s65, 0xffff8000
	s_and_b32 s100, s100, 0x18000
	v_add_u32_e32 v194, s100, v149
	v_add_u32_e32 v195, v194, v157
	v_add_u32_e32 v196, v194, v193
	v_add_u32_e32 v197, v194, v208
	v_add_u32_e32 v194, v194, v209
	ds_read_b128 v[132:135], v195
	ds_read_b128 v[116:119], v195 offset:4096
	ds_read_b128 v[136:139], v196
	ds_read_b128 v[120:123], v196 offset:4096
	ds_read_b128 v[140:143], v197
	ds_read_b128 v[124:127], v197 offset:4096
	ds_read_b128 v[128:131], v194
	ds_read_b128 v[112:115], v194 offset:4096
	s_waitcnt lgkmcnt(0)
	s_branch .LBB0_284

.LBB0_351:
	v_lshl_add_u32 v206, s12, 8, v234
	s_lshl_b32 s12, s13, 10
	v_add_u32_e32 v64, s12, v237
	v_add_u32_e32 v65, s12, v238
	ds_read_b128 v[100:103], v64
	ds_read_b128 v[96:99], v64 offset:16
	ds_read_b128 v[88:91], v65
	ds_read_b128 v[84:87], v65 offset:16
	ds_read_b128 v[76:79], v64 offset:512
	ds_read_b128 v[72:75], v64 offset:528
	ds_read_b128 v[68:71], v65 offset:512
	ds_read_b128 v[64:67], v65 offset:528
	v_lshl_or_b32 v204, s54, 8, v236
	v_or_b32_e32 v208, 16, v206
	v_cndmask_b32_e64 v160, 0, 1, s[18:19]
	v_ashrrev_i32_e32 v205, 31, v204
	s_andn2_b64 vcc, exec, s[46:47]
	v_ashrrev_i32_e32 v207, 31, v206
	v_ashrrev_i32_e32 v209, 31, v208
	v_cmp_ne_u32_e64 s[40:41], 1, v160
	s_cbranch_vccnz .LBB0_401
	v_lshl_add_u64 v[184:185], v[204:205], 2, s[2:3]
	v_lshlrev_b64 v[160:161], 12, v[206:207]
	v_lshlrev_b64 v[162:163], 12, v[208:209]
	v_lshl_add_u64 v[160:161], v[184:185], 0, v[160:161]
	v_lshl_add_u64 v[164:165], v[184:185], 0, v[162:163]
	global_load_dwordx4 v[210:213], v[160:161], off
	global_load_dwordx4 v[218:221], v[160:161], off offset:16
	global_load_dwordx4 v[176:179], v[160:161], off offset:528
	global_load_dwordx4 v[180:183], v[160:161], off offset:512
	global_load_dwordx4 v[168:171], v[164:165], off offset:16
	global_load_dwordx4 v[172:175], v[164:165], off
	s_nop 0
	global_load_dwordx4 v[160:163], v[164:165], off offset:528
	s_nop 0
	global_load_dwordx4 v[164:167], v[164:165], off offset:512
	v_lshlrev_b64 v[186:187], 10, v[206:207]
	v_lshl_add_u64 v[186:187], v[186:187], 0, v[204:205]
	v_lshl_add_u64 v[222:223], v[186:187], 1, s[34:35]
	s_and_b64 vcc, exec, s[40:41]
	s_waitcnt vmcnt(0) lgkmcnt(0)
	v_pk_fma_f32 v[214:215], v[158:159], v[102:103], v[212:213]
	v_pk_fma_f32 v[216:217], v[156:157], v[100:101], v[210:211]
	v_pk_fma_f32 v[210:211], v[154:155], v[98:99], v[220:221]
	v_pk_fma_f32 v[212:213], v[152:153], v[96:97], v[218:219]
	v_cvt_pk_bf16_f32 v218, v216, v217
	v_cvt_pk_bf16_f32 v219, v214, v215
	v_cvt_pk_bf16_f32 v220, v212, v213
	v_cvt_pk_bf16_f32 v221, v210, v211
	global_store_dwordx4 v[222:223], v[218:221], off sc1
	s_cbranch_vccnz .LBB0_354
	s_nop 0
	v_pk_mul_f32 v[220:221], v[90:91], v[214:215]
	v_pk_mul_f32 v[218:219], v[88:89], v[216:217]
	v_pk_mul_f32 v[222:223], v[86:87], v[210:211]
	v_pk_mul_f32 v[224:225], v[84:85], v[212:213]
	v_cvt_pk_bf16_f32 v218, v218, v219
	v_cvt_pk_bf16_f32 v219, v220, v221
	v_cvt_pk_bf16_f32 v220, v224, v225
	v_cvt_pk_bf16_f32 v221, v222, v223
	v_lshl_add_u64 v[222:223], v[186:187], 1, s[74:75]
	global_store_dwordx4 v[222:223], v[218:221], off sc1
.LBB0_354:
	v_or_b32_e32 v186, 0x80, v186
	v_pk_fma_f32 v[182:183], v[150:151], v[78:79], v[182:183]
	v_pk_fma_f32 v[180:181], v[148:149], v[76:77], v[180:181]
	v_pk_fma_f32 v[178:179], v[146:147], v[74:75], v[178:179]
	v_pk_fma_f32 v[176:177], v[144:145], v[72:73], v[176:177]
	v_cvt_pk_bf16_f32 v218, v180, v181
	v_cvt_pk_bf16_f32 v219, v182, v183
	v_cvt_pk_bf16_f32 v220, v176, v177
	v_cvt_pk_bf16_f32 v221, v178, v179
	v_lshl_add_u64 v[222:223], v[186:187], 1, s[34:35]
	s_and_b64 vcc, exec, s[40:41]
	global_store_dwordx4 v[222:223], v[218:221], off sc1
	s_cbranch_vccnz .LBB0_356
	s_nop 0
	v_pk_mul_f32 v[220:221], v[70:71], v[182:183]
	v_pk_mul_f32 v[218:219], v[68:69], v[180:181]
	v_pk_mul_f32 v[222:223], v[66:67], v[178:179]
	v_pk_mul_f32 v[224:225], v[64:65], v[176:177]
	v_cvt_pk_bf16_f32 v218, v218, v219
	v_cvt_pk_bf16_f32 v219, v220, v221
	v_cvt_pk_bf16_f32 v220, v224, v225
	v_cvt_pk_bf16_f32 v221, v222, v223
	v_lshl_add_u64 v[186:187], v[186:187], 1, s[74:75]
	global_store_dwordx4 v[186:187], v[218:221], off sc1

.LBB0_358:
	s_or_b64 exec, exec, s[12:13]
	s_waitcnt lgkmcnt(0)
	v_lshlrev_b64 v[176:177], 10, v[208:209]
	v_lshl_add_u64 v[176:177], v[176:177], 0, v[204:205]
	v_pk_fma_f32 v[174:175], v[142:143], v[102:103], v[174:175]
	v_pk_fma_f32 v[172:173], v[140:141], v[100:101], v[172:173]
	v_pk_fma_f32 v[170:171], v[138:139], v[98:99], v[170:171]
	v_pk_fma_f32 v[168:169], v[136:137], v[96:97], v[168:169]
	v_cvt_pk_bf16_f32 v178, v172, v173
	v_cvt_pk_bf16_f32 v179, v174, v175
	v_cvt_pk_bf16_f32 v180, v168, v169
	v_cvt_pk_bf16_f32 v181, v170, v171
	v_lshl_add_u64 v[182:183], v[176:177], 1, s[34:35]
	s_and_b64 vcc, exec, s[40:41]
	global_store_dwordx4 v[182:183], v[178:181], off sc1
	s_cbranch_vccnz .LBB0_360
	s_nop 0
	v_pk_mul_f32 v[180:181], v[90:91], v[174:175]
	v_pk_mul_f32 v[178:179], v[88:89], v[172:173]
	v_pk_mul_f32 v[182:183], v[86:87], v[170:171]
	v_pk_mul_f32 v[186:187], v[84:85], v[168:169]
	v_cvt_pk_bf16_f32 v178, v178, v179
	v_cvt_pk_bf16_f32 v179, v180, v181
	v_cvt_pk_bf16_f32 v180, v186, v187
	v_cvt_pk_bf16_f32 v181, v182, v183
	v_lshl_add_u64 v[182:183], v[176:177], 1, s[74:75]
	global_store_dwordx4 v[182:183], v[178:181], off sc1
.LBB0_360:
	v_or_b32_e32 v176, 0x80, v176
	v_pk_fma_f32 v[166:167], v[134:135], v[78:79], v[166:167]
	v_pk_fma_f32 v[164:165], v[132:133], v[76:77], v[164:165]
	v_pk_fma_f32 v[162:163], v[130:131], v[74:75], v[162:163]
	v_pk_fma_f32 v[160:161], v[128:129], v[72:73], v[160:161]
	v_cvt_pk_bf16_f32 v178, v164, v165
	v_cvt_pk_bf16_f32 v179, v166, v167
	v_cvt_pk_bf16_f32 v180, v160, v161
	v_cvt_pk_bf16_f32 v181, v162, v163
	v_lshl_add_u64 v[182:183], v[176:177], 1, s[34:35]
	s_and_b64 vcc, exec, s[40:41]
	global_store_dwordx4 v[182:183], v[178:181], off sc1
	s_cbranch_vccnz .LBB0_362
	s_nop 0
	v_pk_mul_f32 v[180:181], v[70:71], v[166:167]
	v_pk_mul_f32 v[178:179], v[68:69], v[164:165]
	v_pk_mul_f32 v[182:183], v[66:67], v[162:163]
	v_pk_mul_f32 v[186:187], v[64:65], v[160:161]
	v_cvt_pk_bf16_f32 v178, v178, v179
	v_cvt_pk_bf16_f32 v179, v180, v181
	v_cvt_pk_bf16_f32 v180, v186, v187
	v_cvt_pk_bf16_f32 v181, v182, v183
	v_lshl_add_u64 v[176:177], v[176:177], 1, s[74:75]
	global_store_dwordx4 v[176:177], v[178:181], off sc1

.LBB0_364:
	s_or_b64 exec, exec, s[12:13]
	v_or_b32_e32 v210, 32, v206
	v_ashrrev_i32_e32 v211, 31, v210
	s_waitcnt lgkmcnt(0)
	v_lshlrev_b64 v[160:161], 12, v[210:211]
	v_or_b32_e32 v186, 48, v206
	v_lshl_add_u64 v[160:161], v[184:185], 0, v[160:161]
	v_ashrrev_i32_e32 v187, 31, v186
	global_load_dwordx4 v[224:227], v[160:161], off offset:16
	global_load_dwordx4 v[214:217], v[160:161], off
	global_load_dwordx4 v[176:179], v[160:161], off offset:528
	global_load_dwordx4 v[180:183], v[160:161], off offset:512
	v_lshlrev_b64 v[160:161], 12, v[186:187]
	v_lshl_add_u64 v[164:165], v[184:185], 0, v[160:161]
	global_load_dwordx4 v[168:171], v[164:165], off offset:16
	global_load_dwordx4 v[172:175], v[164:165], off
	global_load_dwordx4 v[160:163], v[164:165], off offset:528
	s_nop 0
	global_load_dwordx4 v[164:167], v[164:165], off offset:512
	v_lshlrev_b64 v[212:213], 10, v[210:211]
	v_lshl_add_u64 v[212:213], v[212:213], 0, v[204:205]
	v_lshl_add_u64 v[240:241], v[212:213], 1, s[34:35]
	s_and_b64 vcc, exec, s[40:41]
	s_waitcnt vmcnt(6)
	v_pk_fma_f32 v[218:219], v[126:127], v[102:103], v[216:217]
	v_pk_fma_f32 v[220:221], v[124:125], v[100:101], v[214:215]
	v_pk_fma_f32 v[214:215], v[122:123], v[98:99], v[226:227]
	v_pk_fma_f32 v[216:217], v[120:121], v[96:97], v[224:225]
	v_cvt_pk_bf16_f32 v224, v220, v221
	v_cvt_pk_bf16_f32 v225, v218, v219
	v_cvt_pk_bf16_f32 v226, v216, v217
	v_cvt_pk_bf16_f32 v227, v214, v215
	global_store_dwordx4 v[240:241], v[224:227], off sc1
	s_cbranch_vccnz .LBB0_366
	s_nop 0
	v_pk_mul_f32 v[226:227], v[90:91], v[218:219]
	v_pk_mul_f32 v[224:225], v[88:89], v[220:221]
	v_pk_mul_f32 v[240:241], v[86:87], v[214:215]
	v_pk_mul_f32 v[242:243], v[84:85], v[216:217]
	v_cvt_pk_bf16_f32 v224, v224, v225
	v_cvt_pk_bf16_f32 v225, v226, v227
	v_cvt_pk_bf16_f32 v226, v242, v243
	v_cvt_pk_bf16_f32 v227, v240, v241
	v_lshl_add_u64 v[240:241], v[212:213], 1, s[74:75]
	global_store_dwordx4 v[240:241], v[224:227], off sc1
.LBB0_366:
	v_or_b32_e32 v212, 0x80, v212
	s_waitcnt vmcnt(5)
	v_pk_fma_f32 v[182:183], v[118:119], v[78:79], v[182:183]
	v_pk_fma_f32 v[180:181], v[116:117], v[76:77], v[180:181]
	v_pk_fma_f32 v[178:179], v[114:115], v[74:75], v[178:179]
	v_pk_fma_f32 v[176:177], v[112:113], v[72:73], v[176:177]
	v_cvt_pk_bf16_f32 v224, v180, v181
	v_cvt_pk_bf16_f32 v225, v182, v183
	v_cvt_pk_bf16_f32 v226, v176, v177
	v_cvt_pk_bf16_f32 v227, v178, v179
	v_lshl_add_u64 v[240:241], v[212:213], 1, s[34:35]
	s_and_b64 vcc, exec, s[40:41]
	global_store_dwordx4 v[240:241], v[224:227], off sc1
	s_cbranch_vccnz .LBB0_368
	s_nop 0
	v_pk_mul_f32 v[226:227], v[70:71], v[182:183]
	v_pk_mul_f32 v[224:225], v[68:69], v[180:181]
	v_pk_mul_f32 v[240:241], v[66:67], v[178:179]
	v_pk_mul_f32 v[242:243], v[64:65], v[176:177]
	v_cvt_pk_bf16_f32 v224, v224, v225
	v_cvt_pk_bf16_f32 v225, v226, v227
	v_cvt_pk_bf16_f32 v226, v242, v243
	v_cvt_pk_bf16_f32 v227, v240, v241
	v_lshl_add_u64 v[212:213], v[212:213], 1, s[74:75]
	global_store_dwordx4 v[212:213], v[224:227], off sc1

.LBB0_370:
	s_or_b64 exec, exec, s[12:13]
	s_waitcnt lgkmcnt(0)
	v_lshlrev_b64 v[176:177], 10, v[186:187]
	v_lshl_add_u64 v[176:177], v[176:177], 0, v[204:205]
	s_waitcnt vmcnt(4)
	v_pk_fma_f32 v[174:175], v[110:111], v[102:103], v[174:175]
	v_pk_fma_f32 v[172:173], v[108:109], v[100:101], v[172:173]
	v_pk_fma_f32 v[170:171], v[106:107], v[98:99], v[170:171]
	v_pk_fma_f32 v[168:169], v[104:105], v[96:97], v[168:169]
	v_cvt_pk_bf16_f32 v178, v172, v173
	v_cvt_pk_bf16_f32 v179, v174, v175
	v_cvt_pk_bf16_f32 v180, v168, v169
	v_cvt_pk_bf16_f32 v181, v170, v171
	v_lshl_add_u64 v[182:183], v[176:177], 1, s[34:35]
	s_and_b64 vcc, exec, s[40:41]
	global_store_dwordx4 v[182:183], v[178:181], off sc1
	s_cbranch_vccnz .LBB0_372
	s_nop 0
	v_pk_mul_f32 v[180:181], v[90:91], v[174:175]
	v_pk_mul_f32 v[178:179], v[88:89], v[172:173]
	v_pk_mul_f32 v[182:183], v[86:87], v[170:171]
	v_pk_mul_f32 v[210:211], v[84:85], v[168:169]
	v_cvt_pk_bf16_f32 v178, v178, v179
	v_cvt_pk_bf16_f32 v179, v180, v181
	v_cvt_pk_bf16_f32 v180, v210, v211
	v_cvt_pk_bf16_f32 v181, v182, v183
	v_lshl_add_u64 v[182:183], v[176:177], 1, s[74:75]
	global_store_dwordx4 v[182:183], v[178:181], off sc1
.LBB0_372:
	v_or_b32_e32 v176, 0x80, v176
	s_waitcnt vmcnt(3)
	v_pk_fma_f32 v[166:167], v[94:95], v[78:79], v[166:167]
	v_pk_fma_f32 v[164:165], v[92:93], v[76:77], v[164:165]
	v_pk_fma_f32 v[162:163], v[82:83], v[74:75], v[162:163]
	v_pk_fma_f32 v[160:161], v[80:81], v[72:73], v[160:161]
	v_cvt_pk_bf16_f32 v178, v164, v165
	v_cvt_pk_bf16_f32 v179, v166, v167
	v_cvt_pk_bf16_f32 v180, v160, v161
	v_cvt_pk_bf16_f32 v181, v162, v163
	v_lshl_add_u64 v[182:183], v[176:177], 1, s[34:35]
	s_and_b64 vcc, exec, s[40:41]
	global_store_dwordx4 v[182:183], v[178:181], off sc1
	s_cbranch_vccnz .LBB0_374
	s_nop 0
	v_pk_mul_f32 v[180:181], v[70:71], v[166:167]
	v_pk_mul_f32 v[178:179], v[68:69], v[164:165]
	v_pk_mul_f32 v[182:183], v[66:67], v[162:163]
	v_pk_mul_f32 v[210:211], v[64:65], v[160:161]
	v_cvt_pk_bf16_f32 v178, v178, v179
	v_cvt_pk_bf16_f32 v179, v180, v181
	v_cvt_pk_bf16_f32 v180, v210, v211
	v_cvt_pk_bf16_f32 v181, v182, v183
	v_lshl_add_u64 v[176:177], v[176:177], 1, s[74:75]
	global_store_dwordx4 v[176:177], v[178:181], off sc1

.LBB0_376:
	s_or_b64 exec, exec, s[12:13]
	v_add_u32_e32 v210, 0x80, v206
	v_ashrrev_i32_e32 v211, 31, v210
	s_waitcnt lgkmcnt(0)
	v_lshlrev_b64 v[160:161], 12, v[210:211]
	v_add_u32_e32 v186, 0x90, v206
	v_lshl_add_u64 v[160:161], v[184:185], 0, v[160:161]
	v_ashrrev_i32_e32 v187, 31, v186
	global_load_dwordx4 v[224:227], v[160:161], off offset:16
	global_load_dwordx4 v[214:217], v[160:161], off
	global_load_dwordx4 v[176:179], v[160:161], off offset:528
	global_load_dwordx4 v[180:183], v[160:161], off offset:512
	v_lshlrev_b64 v[160:161], 12, v[186:187]
	v_lshl_add_u64 v[164:165], v[184:185], 0, v[160:161]
	global_load_dwordx4 v[168:171], v[164:165], off offset:16
	global_load_dwordx4 v[172:175], v[164:165], off
	global_load_dwordx4 v[160:163], v[164:165], off offset:528
	s_nop 0
	global_load_dwordx4 v[164:167], v[164:165], off offset:512
	v_lshlrev_b64 v[212:213], 10, v[210:211]
	v_lshl_add_u64 v[212:213], v[212:213], 0, v[204:205]
	v_lshl_add_u64 v[240:241], v[212:213], 1, s[34:35]
	s_and_b64 vcc, exec, s[40:41]
	s_waitcnt vmcnt(6)
	v_pk_fma_f32 v[218:219], v[62:63], v[102:103], v[216:217]
	v_pk_fma_f32 v[220:221], v[60:61], v[100:101], v[214:215]
	v_pk_fma_f32 v[214:215], v[58:59], v[98:99], v[226:227]
	v_pk_fma_f32 v[216:217], v[56:57], v[96:97], v[224:225]
	v_cvt_pk_bf16_f32 v224, v220, v221
	v_cvt_pk_bf16_f32 v225, v218, v219
	v_cvt_pk_bf16_f32 v226, v216, v217
	v_cvt_pk_bf16_f32 v227, v214, v215
	global_store_dwordx4 v[240:241], v[224:227], off sc1
	s_cbranch_vccnz .LBB0_378
	s_nop 0
	v_pk_mul_f32 v[226:227], v[90:91], v[218:219]
	v_pk_mul_f32 v[224:225], v[88:89], v[220:221]
	v_pk_mul_f32 v[240:241], v[86:87], v[214:215]
	v_pk_mul_f32 v[242:243], v[84:85], v[216:217]
	v_cvt_pk_bf16_f32 v224, v224, v225
	v_cvt_pk_bf16_f32 v225, v226, v227
	v_cvt_pk_bf16_f32 v226, v242, v243
	v_cvt_pk_bf16_f32 v227, v240, v241
	v_lshl_add_u64 v[240:241], v[212:213], 1, s[74:75]
	global_store_dwordx4 v[240:241], v[224:227], off sc1
.LBB0_378:
	v_or_b32_e32 v212, 0x80, v212
	s_waitcnt vmcnt(5)
	v_pk_fma_f32 v[182:183], v[54:55], v[78:79], v[182:183]
	v_pk_fma_f32 v[180:181], v[52:53], v[76:77], v[180:181]
	v_pk_fma_f32 v[178:179], v[50:51], v[74:75], v[178:179]
	v_pk_fma_f32 v[176:177], v[48:49], v[72:73], v[176:177]
	v_cvt_pk_bf16_f32 v224, v180, v181
	v_cvt_pk_bf16_f32 v225, v182, v183
	v_cvt_pk_bf16_f32 v226, v176, v177
	v_cvt_pk_bf16_f32 v227, v178, v179
	v_lshl_add_u64 v[240:241], v[212:213], 1, s[34:35]
	s_and_b64 vcc, exec, s[40:41]
	global_store_dwordx4 v[240:241], v[224:227], off sc1
	s_cbranch_vccnz .LBB0_380
	s_nop 0
	v_pk_mul_f32 v[226:227], v[70:71], v[182:183]
	v_pk_mul_f32 v[224:225], v[68:69], v[180:181]
	v_pk_mul_f32 v[240:241], v[66:67], v[178:179]
	v_pk_mul_f32 v[242:243], v[64:65], v[176:177]
	v_cvt_pk_bf16_f32 v224, v224, v225
	v_cvt_pk_bf16_f32 v225, v226, v227
	v_cvt_pk_bf16_f32 v226, v242, v243
	v_cvt_pk_bf16_f32 v227, v240, v241
	v_lshl_add_u64 v[212:213], v[212:213], 1, s[74:75]
	global_store_dwordx4 v[212:213], v[224:227], off sc1

.LBB0_382:
	s_or_b64 exec, exec, s[12:13]
	s_waitcnt lgkmcnt(0)
	v_lshlrev_b64 v[176:177], 10, v[186:187]
	v_lshl_add_u64 v[176:177], v[176:177], 0, v[204:205]
	s_waitcnt vmcnt(4)
	v_pk_fma_f32 v[174:175], v[46:47], v[102:103], v[174:175]
	v_pk_fma_f32 v[172:173], v[44:45], v[100:101], v[172:173]
	v_pk_fma_f32 v[170:171], v[42:43], v[98:99], v[170:171]
	v_pk_fma_f32 v[168:169], v[40:41], v[96:97], v[168:169]
	v_cvt_pk_bf16_f32 v178, v172, v173
	v_cvt_pk_bf16_f32 v179, v174, v175
	v_cvt_pk_bf16_f32 v180, v168, v169
	v_cvt_pk_bf16_f32 v181, v170, v171
	v_lshl_add_u64 v[182:183], v[176:177], 1, s[34:35]
	s_and_b64 vcc, exec, s[40:41]
	global_store_dwordx4 v[182:183], v[178:181], off sc1
	s_cbranch_vccnz .LBB0_384
	s_nop 0
	v_pk_mul_f32 v[180:181], v[90:91], v[174:175]
	v_pk_mul_f32 v[178:179], v[88:89], v[172:173]
	v_pk_mul_f32 v[182:183], v[86:87], v[170:171]
	v_pk_mul_f32 v[210:211], v[84:85], v[168:169]
	v_cvt_pk_bf16_f32 v178, v178, v179
	v_cvt_pk_bf16_f32 v179, v180, v181
	v_cvt_pk_bf16_f32 v180, v210, v211
	v_cvt_pk_bf16_f32 v181, v182, v183
	v_lshl_add_u64 v[182:183], v[176:177], 1, s[74:75]
	global_store_dwordx4 v[182:183], v[178:181], off sc1
.LBB0_384:
	v_or_b32_e32 v176, 0x80, v176
	s_waitcnt vmcnt(3)
	v_pk_fma_f32 v[166:167], v[38:39], v[78:79], v[166:167]
	v_pk_fma_f32 v[164:165], v[36:37], v[76:77], v[164:165]
	v_pk_fma_f32 v[162:163], v[34:35], v[74:75], v[162:163]
	v_pk_fma_f32 v[160:161], v[32:33], v[72:73], v[160:161]
	v_cvt_pk_bf16_f32 v178, v164, v165
	v_cvt_pk_bf16_f32 v179, v166, v167
	v_cvt_pk_bf16_f32 v180, v160, v161
	v_cvt_pk_bf16_f32 v181, v162, v163
	v_lshl_add_u64 v[182:183], v[176:177], 1, s[34:35]
	s_and_b64 vcc, exec, s[40:41]
	global_store_dwordx4 v[182:183], v[178:181], off sc1
	s_cbranch_vccnz .LBB0_386
	s_nop 0
	v_pk_mul_f32 v[180:181], v[70:71], v[166:167]
	v_pk_mul_f32 v[178:179], v[68:69], v[164:165]
	v_pk_mul_f32 v[182:183], v[66:67], v[162:163]
	v_pk_mul_f32 v[210:211], v[64:65], v[160:161]
	v_cvt_pk_bf16_f32 v178, v178, v179
	v_cvt_pk_bf16_f32 v179, v180, v181
	v_cvt_pk_bf16_f32 v180, v210, v211
	v_cvt_pk_bf16_f32 v181, v182, v183
	v_lshl_add_u64 v[176:177], v[176:177], 1, s[74:75]
	global_store_dwordx4 v[176:177], v[178:181], off sc1

.LBB0_388:
	s_or_b64 exec, exec, s[12:13]
	v_add_u32_e32 v210, 0xa0, v206
	v_ashrrev_i32_e32 v211, 31, v210
	s_waitcnt lgkmcnt(0)
	v_lshlrev_b64 v[160:161], 12, v[210:211]
	v_add_u32_e32 v186, 0xb0, v206
	v_lshl_add_u64 v[160:161], v[184:185], 0, v[160:161]
	v_ashrrev_i32_e32 v187, 31, v186
	global_load_dwordx4 v[224:227], v[160:161], off offset:16
	global_load_dwordx4 v[212:215], v[160:161], off
	global_load_dwordx4 v[176:179], v[160:161], off offset:528
	global_load_dwordx4 v[180:183], v[160:161], off offset:512
	v_lshlrev_b64 v[160:161], 12, v[186:187]
	v_lshl_add_u64 v[164:165], v[184:185], 0, v[160:161]
	global_load_dwordx4 v[168:171], v[164:165], off offset:16
	global_load_dwordx4 v[172:175], v[164:165], off
	global_load_dwordx4 v[160:163], v[164:165], off offset:528
	s_nop 0
	global_load_dwordx4 v[164:167], v[164:165], off offset:512
	v_lshlrev_b64 v[184:185], 10, v[210:211]
	v_lshl_add_u64 v[184:185], v[184:185], 0, v[204:205]
	v_lshl_add_u64 v[220:221], v[184:185], 1, s[34:35]
	s_and_b64 vcc, exec, s[40:41]
	s_waitcnt vmcnt(6)
	v_pk_fma_f32 v[216:217], v[30:31], v[102:103], v[214:215]
	v_pk_fma_f32 v[218:219], v[28:29], v[100:101], v[212:213]
	v_pk_fma_f32 v[212:213], v[26:27], v[98:99], v[226:227]
	v_pk_fma_f32 v[214:215], v[24:25], v[96:97], v[224:225]
	v_cvt_pk_bf16_f32 v224, v218, v219
	v_cvt_pk_bf16_f32 v225, v216, v217
	v_cvt_pk_bf16_f32 v226, v214, v215
	v_cvt_pk_bf16_f32 v227, v212, v213
	global_store_dwordx4 v[220:221], v[224:227], off sc1
	s_cbranch_vccnz .LBB0_390
	v_pk_mul_f32 v[220:221], v[90:91], v[216:217]
	v_pk_mul_f32 v[224:225], v[88:89], v[218:219]
	v_pk_mul_f32 v[240:241], v[86:87], v[212:213]
	v_pk_mul_f32 v[226:227], v[84:85], v[214:215]
	v_cvt_pk_bf16_f32 v224, v224, v225
	v_cvt_pk_bf16_f32 v225, v220, v221
	v_cvt_pk_bf16_f32 v226, v226, v227
	v_cvt_pk_bf16_f32 v227, v240, v241
	v_lshl_add_u64 v[220:221], v[184:185], 1, s[74:75]
	global_store_dwordx4 v[220:221], v[224:227], off sc1
.LBB0_390:
	v_or_b32_e32 v184, 0x80, v184
	s_waitcnt vmcnt(5)
	v_pk_fma_f32 v[182:183], v[22:23], v[78:79], v[182:183]
	v_pk_fma_f32 v[180:181], v[20:21], v[76:77], v[180:181]
	v_pk_fma_f32 v[178:179], v[18:19], v[74:75], v[178:179]
	v_pk_fma_f32 v[176:177], v[16:17], v[72:73], v[176:177]
	v_cvt_pk_bf16_f32 v224, v180, v181
	v_cvt_pk_bf16_f32 v225, v182, v183
	v_cvt_pk_bf16_f32 v226, v176, v177
	v_cvt_pk_bf16_f32 v227, v178, v179
	v_lshl_add_u64 v[220:221], v[184:185], 1, s[34:35]
	s_and_b64 vcc, exec, s[40:41]
	global_store_dwordx4 v[220:221], v[224:227], off sc1
	s_cbranch_vccnz .LBB0_392
	v_pk_mul_f32 v[220:221], v[70:71], v[182:183]
	v_pk_mul_f32 v[224:225], v[68:69], v[180:181]
	v_pk_mul_f32 v[240:241], v[66:67], v[178:179]
	v_pk_mul_f32 v[226:227], v[64:65], v[176:177]
	v_cvt_pk_bf16_f32 v224, v224, v225
	v_cvt_pk_bf16_f32 v225, v220, v221
	v_cvt_pk_bf16_f32 v226, v226, v227
	v_cvt_pk_bf16_f32 v227, v240, v241
	v_lshl_add_u64 v[184:185], v[184:185], 1, s[74:75]
	global_store_dwordx4 v[184:185], v[224:227], off sc1

.LBB0_394:
	s_or_b64 exec, exec, s[12:13]
	s_waitcnt lgkmcnt(0)
	v_lshlrev_b64 v[176:177], 10, v[186:187]
	v_lshl_add_u64 v[176:177], v[176:177], 0, v[204:205]
	s_waitcnt vmcnt(4)
	v_pk_fma_f32 v[174:175], v[14:15], v[102:103], v[174:175]
	v_pk_fma_f32 v[172:173], v[12:13], v[100:101], v[172:173]
	v_pk_fma_f32 v[170:171], v[10:11], v[98:99], v[170:171]
	v_pk_fma_f32 v[168:169], v[8:9], v[96:97], v[168:169]
	v_cvt_pk_bf16_f32 v178, v172, v173
	v_cvt_pk_bf16_f32 v179, v174, v175
	v_cvt_pk_bf16_f32 v180, v168, v169
	v_cvt_pk_bf16_f32 v181, v170, v171
	v_lshl_add_u64 v[182:183], v[176:177], 1, s[34:35]
	s_and_b64 vcc, exec, s[40:41]
	global_store_dwordx4 v[182:183], v[178:181], off sc1
	s_cbranch_vccnz .LBB0_396
	s_nop 0
	v_pk_mul_f32 v[180:181], v[90:91], v[174:175]
	v_pk_mul_f32 v[178:179], v[88:89], v[172:173]
	v_pk_mul_f32 v[182:183], v[86:87], v[170:171]
	v_pk_mul_f32 v[184:185], v[84:85], v[168:169]
	v_cvt_pk_bf16_f32 v178, v178, v179
	v_cvt_pk_bf16_f32 v179, v180, v181
	v_cvt_pk_bf16_f32 v180, v184, v185
	v_cvt_pk_bf16_f32 v181, v182, v183
	v_lshl_add_u64 v[182:183], v[176:177], 1, s[74:75]
	global_store_dwordx4 v[182:183], v[178:181], off sc1
.LBB0_396:
	v_or_b32_e32 v176, 0x80, v176
	s_waitcnt vmcnt(3)
	v_pk_fma_f32 v[166:167], v[6:7], v[78:79], v[166:167]
	v_pk_fma_f32 v[164:165], v[4:5], v[76:77], v[164:165]
	v_pk_fma_f32 v[162:163], v[2:3], v[74:75], v[162:163]
	v_pk_fma_f32 v[160:161], v[0:1], v[72:73], v[160:161]
	v_cvt_pk_bf16_f32 v178, v164, v165
	v_cvt_pk_bf16_f32 v179, v166, v167
	v_cvt_pk_bf16_f32 v180, v160, v161
	v_cvt_pk_bf16_f32 v181, v162, v163
	v_lshl_add_u64 v[182:183], v[176:177], 1, s[34:35]
	s_and_b64 vcc, exec, s[40:41]
	global_store_dwordx4 v[182:183], v[178:181], off sc1
	s_cbranch_vccnz .LBB0_398
	s_nop 0
	v_pk_mul_f32 v[180:181], v[70:71], v[166:167]
	v_pk_mul_f32 v[178:179], v[68:69], v[164:165]
	v_pk_mul_f32 v[182:183], v[66:67], v[162:163]
	v_pk_mul_f32 v[184:185], v[64:65], v[160:161]
	v_cvt_pk_bf16_f32 v178, v178, v179
	v_cvt_pk_bf16_f32 v179, v180, v181
	v_cvt_pk_bf16_f32 v180, v184, v185
	v_cvt_pk_bf16_f32 v181, v182, v183
	v_lshl_add_u64 v[176:177], v[176:177], 1, s[74:75]
	global_store_dwordx4 v[176:177], v[178:181], off sc1

.LBB0_401:
	s_mov_b64 s[12:13], 0
	s_cbranch_execz .LBB0_399
	v_lshl_add_u64 v[210:211], v[204:205], 1, s[34:35]
	s_waitcnt lgkmcnt(0)
	v_lshlrev_b64 v[160:161], 11, v[206:207]
	v_or_b32_e32 v216, 32, v206
	v_lshl_add_u64 v[240:241], v[210:211], 0, v[160:161]
	v_lshlrev_b64 v[160:161], 11, v[208:209]
	v_ashrrev_i32_e32 v217, 31, v216
	v_or_b32_e32 v212, 48, v206
	v_lshl_add_u64 v[220:221], v[210:211], 0, v[160:161]
	v_lshlrev_b64 v[160:161], 11, v[216:217]
	v_ashrrev_i32_e32 v213, 31, v212
	v_lshl_add_u64 v[218:219], v[210:211], 0, v[160:161]
	v_lshlrev_b64 v[160:161], 11, v[212:213]
	v_lshl_add_u64 v[214:215], v[210:211], 0, v[160:161]
	global_load_dwordx4 v[222:225], v[240:241], off nt
	global_load_dwordx4 v[184:187], v[240:241], off offset:256 nt
	global_load_dwordx4 v[180:183], v[220:221], off nt
	global_load_dwordx4 v[176:179], v[220:221], off offset:256 nt
	global_load_dwordx4 v[172:175], v[218:219], off nt
	global_load_dwordx4 v[168:171], v[218:219], off offset:256 nt
	global_load_dwordx4 v[164:167], v[214:215], off nt
	global_load_dwordx4 v[160:163], v[214:215], off offset:256 nt
	s_waitcnt vmcnt(0)
	v_lshlrev_b32_e32 v226, 16, v222
	v_and_b32_e32 v227, 0xffff0000, v222
	v_lshlrev_b32_e32 v242, 16, v223
	v_and_b32_e32 v243, 0xffff0000, v223
	v_lshlrev_b32_e32 v244, 16, v224
	v_and_b32_e32 v245, 0xffff0000, v224
	v_lshlrev_b32_e32 v224, 16, v225
	v_and_b32_e32 v225, 0xffff0000, v225
	v_lshlrev_b64 v[222:223], 10, v[206:207]
	v_pk_fma_f32 v[158:159], v[158:159], v[102:103], v[242:243]
	v_pk_fma_f32 v[156:157], v[156:157], v[100:101], v[226:227]
	v_pk_fma_f32 v[154:155], v[154:155], v[98:99], v[224:225]
	v_pk_fma_f32 v[152:153], v[152:153], v[96:97], v[244:245]
	v_lshl_add_u64 v[222:223], v[222:223], 0, v[204:205]
	v_cvt_pk_bf16_f32 v224, v156, v157
	v_cvt_pk_bf16_f32 v225, v158, v159
	v_cvt_pk_bf16_f32 v226, v152, v153
	v_cvt_pk_bf16_f32 v227, v154, v155
	s_and_b64 vcc, exec, s[40:41]
	global_store_dwordx4 v[240:241], v[224:227], off sc1
	s_cbranch_vccnz .LBB0_404
	s_nop 0
	v_pk_mul_f32 v[226:227], v[90:91], v[158:159]
	v_pk_mul_f32 v[224:225], v[88:89], v[156:157]
	v_pk_mul_f32 v[240:241], v[86:87], v[154:155]
	v_pk_mul_f32 v[242:243], v[84:85], v[152:153]
	v_cvt_pk_bf16_f32 v224, v224, v225
	v_cvt_pk_bf16_f32 v225, v226, v227
	v_cvt_pk_bf16_f32 v226, v242, v243
	v_cvt_pk_bf16_f32 v227, v240, v241
	v_lshl_add_u64 v[240:241], v[222:223], 1, s[74:75]
	global_store_dwordx4 v[240:241], v[224:227], off sc1
.LBB0_404:
	s_nop 1
	v_lshlrev_b32_e32 v224, 16, v184
	v_and_b32_e32 v225, 0xffff0000, v184
	v_lshlrev_b32_e32 v184, 16, v185
	v_and_b32_e32 v185, 0xffff0000, v185
	v_lshlrev_b32_e32 v226, 16, v186
	v_and_b32_e32 v227, 0xffff0000, v186
	v_lshlrev_b32_e32 v186, 16, v187
	v_and_b32_e32 v187, 0xffff0000, v187
	v_or_b32_e32 v222, 0x80, v222
	v_pk_fma_f32 v[150:151], v[150:151], v[78:79], v[184:185]
	v_pk_fma_f32 v[148:149], v[148:149], v[76:77], v[224:225]
	v_pk_fma_f32 v[146:147], v[146:147], v[74:75], v[186:187]
	v_pk_fma_f32 v[144:145], v[144:145], v[72:73], v[226:227]
	v_cvt_pk_bf16_f32 v184, v148, v149
	v_cvt_pk_bf16_f32 v185, v150, v151
	v_cvt_pk_bf16_f32 v186, v144, v145
	v_cvt_pk_bf16_f32 v187, v146, v147
	v_lshl_add_u64 v[224:225], v[222:223], 1, s[34:35]
	s_and_b64 vcc, exec, s[40:41]
	global_store_dwordx4 v[224:225], v[184:187], off sc1
	s_cbranch_vccnz .LBB0_406
	s_nop 0
	v_pk_mul_f32 v[186:187], v[70:71], v[150:151]
	v_pk_mul_f32 v[184:185], v[68:69], v[148:149]
	v_pk_mul_f32 v[224:225], v[66:67], v[146:147]
	v_pk_mul_f32 v[226:227], v[64:65], v[144:145]
	v_cvt_pk_bf16_f32 v184, v184, v185
	v_cvt_pk_bf16_f32 v185, v186, v187
	v_cvt_pk_bf16_f32 v186, v226, v227
	v_cvt_pk_bf16_f32 v187, v224, v225
	v_lshl_add_u64 v[222:223], v[222:223], 1, s[74:75]
	global_store_dwordx4 v[222:223], v[184:187], off sc1

.LBB0_408:
	s_or_b64 exec, exec, s[12:13]
	v_lshlrev_b32_e32 v146, 16, v180
	v_and_b32_e32 v147, 0xffff0000, v180
	v_lshlrev_b32_e32 v148, 16, v181
	v_and_b32_e32 v149, 0xffff0000, v181
	v_lshlrev_b32_e32 v150, 16, v182
	v_and_b32_e32 v151, 0xffff0000, v182
	v_lshlrev_b32_e32 v152, 16, v183
	v_and_b32_e32 v153, 0xffff0000, v183
	s_waitcnt lgkmcnt(0)
	v_lshlrev_b64 v[144:145], 10, v[208:209]
	v_pk_fma_f32 v[142:143], v[142:143], v[102:103], v[148:149]
	v_pk_fma_f32 v[140:141], v[140:141], v[100:101], v[146:147]
	v_pk_fma_f32 v[138:139], v[138:139], v[98:99], v[152:153]
	v_pk_fma_f32 v[136:137], v[136:137], v[96:97], v[150:151]
	v_lshl_add_u64 v[144:145], v[144:145], 0, v[204:205]
	v_cvt_pk_bf16_f32 v146, v140, v141
	v_cvt_pk_bf16_f32 v147, v142, v143
	v_cvt_pk_bf16_f32 v148, v136, v137
	v_cvt_pk_bf16_f32 v149, v138, v139
	s_and_b64 vcc, exec, s[40:41]
	global_store_dwordx4 v[220:221], v[146:149], off sc1
	s_cbranch_vccnz .LBB0_410
	s_nop 0
	v_pk_mul_f32 v[148:149], v[90:91], v[142:143]
	v_pk_mul_f32 v[146:147], v[88:89], v[140:141]
	v_pk_mul_f32 v[150:151], v[86:87], v[138:139]
	v_pk_mul_f32 v[152:153], v[84:85], v[136:137]
	v_cvt_pk_bf16_f32 v146, v146, v147
	v_cvt_pk_bf16_f32 v147, v148, v149
	v_cvt_pk_bf16_f32 v148, v152, v153
	v_cvt_pk_bf16_f32 v149, v150, v151
	v_lshl_add_u64 v[150:151], v[144:145], 1, s[74:75]
	global_store_dwordx4 v[150:151], v[146:149], off sc1
.LBB0_410:
	s_nop 1
	v_lshlrev_b32_e32 v146, 16, v176
	v_and_b32_e32 v147, 0xffff0000, v176
	v_lshlrev_b32_e32 v148, 16, v177
	v_and_b32_e32 v149, 0xffff0000, v177
	v_lshlrev_b32_e32 v150, 16, v178
	v_and_b32_e32 v151, 0xffff0000, v178
	v_lshlrev_b32_e32 v152, 16, v179
	v_and_b32_e32 v153, 0xffff0000, v179
	v_or_b32_e32 v144, 0x80, v144
	v_pk_fma_f32 v[134:135], v[134:135], v[78:79], v[148:149]
	v_pk_fma_f32 v[132:133], v[132:133], v[76:77], v[146:147]
	v_pk_fma_f32 v[130:131], v[130:131], v[74:75], v[152:153]
	v_pk_fma_f32 v[128:129], v[128:129], v[72:73], v[150:151]
	v_cvt_pk_bf16_f32 v146, v132, v133
	v_cvt_pk_bf16_f32 v147, v134, v135
	v_cvt_pk_bf16_f32 v148, v128, v129
	v_cvt_pk_bf16_f32 v149, v130, v131
	v_lshl_add_u64 v[150:151], v[144:145], 1, s[34:35]
	s_and_b64 vcc, exec, s[40:41]
	global_store_dwordx4 v[150:151], v[146:149], off sc1
	s_cbranch_vccnz .LBB0_412
	s_nop 0
	v_pk_mul_f32 v[148:149], v[70:71], v[134:135]
	v_pk_mul_f32 v[146:147], v[68:69], v[132:133]
	v_pk_mul_f32 v[150:151], v[66:67], v[130:131]
	v_pk_mul_f32 v[152:153], v[64:65], v[128:129]
	v_cvt_pk_bf16_f32 v146, v146, v147
	v_cvt_pk_bf16_f32 v147, v148, v149
	v_cvt_pk_bf16_f32 v148, v152, v153
	v_cvt_pk_bf16_f32 v149, v150, v151
	v_lshl_add_u64 v[144:145], v[144:145], 1, s[74:75]
	global_store_dwordx4 v[144:145], v[146:149], off sc1

.LBB0_414:
	s_or_b64 exec, exec, s[12:13]
	v_add_u32_e32 v148, 0x80, v206
	v_ashrrev_i32_e32 v149, 31, v148
	v_add_u32_e32 v144, 0x90, v206
	s_waitcnt lgkmcnt(0)
	v_lshlrev_b64 v[128:129], 11, v[148:149]
	v_ashrrev_i32_e32 v145, 31, v144
	v_lshl_add_u64 v[150:151], v[210:211], 0, v[128:129]
	v_lshlrev_b64 v[128:129], 11, v[144:145]
	v_lshl_add_u64 v[146:147], v[210:211], 0, v[128:129]
	global_load_dwordx4 v[140:143], v[150:151], off nt
	global_load_dwordx4 v[136:139], v[150:151], off offset:256 nt
	global_load_dwordx4 v[132:135], v[146:147], off nt
	global_load_dwordx4 v[128:131], v[146:147], off offset:256 nt
	v_lshlrev_b32_e32 v156, 16, v172
	v_and_b32_e32 v157, 0xffff0000, v172
	v_lshlrev_b32_e32 v158, 16, v173
	v_and_b32_e32 v159, 0xffff0000, v173
	v_lshlrev_b32_e32 v172, 16, v174
	v_and_b32_e32 v173, 0xffff0000, v174
	v_lshlrev_b32_e32 v174, 16, v175
	v_and_b32_e32 v175, 0xffff0000, v175
	v_lshlrev_b64 v[152:153], 10, v[216:217]
	v_pk_fma_f32 v[126:127], v[126:127], v[102:103], v[158:159]
	v_pk_fma_f32 v[124:125], v[124:125], v[100:101], v[156:157]
	v_pk_fma_f32 v[122:123], v[122:123], v[98:99], v[174:175]
	v_pk_fma_f32 v[120:121], v[120:121], v[96:97], v[172:173]
	v_lshl_add_u64 v[152:153], v[152:153], 0, v[204:205]
	v_cvt_pk_bf16_f32 v156, v124, v125
	v_cvt_pk_bf16_f32 v157, v126, v127
	v_cvt_pk_bf16_f32 v158, v120, v121
	v_cvt_pk_bf16_f32 v159, v122, v123
	s_and_b64 vcc, exec, s[40:41]
	global_store_dwordx4 v[218:219], v[156:159], off sc1
	s_cbranch_vccnz .LBB0_416
	s_nop 0
	v_pk_mul_f32 v[158:159], v[90:91], v[126:127]
	v_pk_mul_f32 v[156:157], v[88:89], v[124:125]
	v_pk_mul_f32 v[172:173], v[86:87], v[122:123]
	v_pk_mul_f32 v[174:175], v[84:85], v[120:121]
	v_cvt_pk_bf16_f32 v156, v156, v157
	v_cvt_pk_bf16_f32 v157, v158, v159
	v_cvt_pk_bf16_f32 v158, v174, v175
	v_cvt_pk_bf16_f32 v159, v172, v173
	v_lshl_add_u64 v[172:173], v[152:153], 1, s[74:75]
	global_store_dwordx4 v[172:173], v[156:159], off sc1
.LBB0_416:
	s_nop 1
	v_lshlrev_b32_e32 v156, 16, v168
	v_and_b32_e32 v157, 0xffff0000, v168
	v_lshlrev_b32_e32 v158, 16, v169
	v_and_b32_e32 v159, 0xffff0000, v169
	v_lshlrev_b32_e32 v168, 16, v170
	v_and_b32_e32 v169, 0xffff0000, v170
	v_lshlrev_b32_e32 v170, 16, v171
	v_and_b32_e32 v171, 0xffff0000, v171
	v_or_b32_e32 v152, 0x80, v152
	v_pk_fma_f32 v[118:119], v[118:119], v[78:79], v[158:159]
	v_pk_fma_f32 v[116:117], v[116:117], v[76:77], v[156:157]
	v_pk_fma_f32 v[114:115], v[114:115], v[74:75], v[170:171]
	v_pk_fma_f32 v[112:113], v[112:113], v[72:73], v[168:169]
	v_cvt_pk_bf16_f32 v156, v116, v117
	v_cvt_pk_bf16_f32 v157, v118, v119
	v_cvt_pk_bf16_f32 v158, v112, v113
	v_cvt_pk_bf16_f32 v159, v114, v115
	v_lshl_add_u64 v[168:169], v[152:153], 1, s[34:35]
	s_and_b64 vcc, exec, s[40:41]
	global_store_dwordx4 v[168:169], v[156:159], off sc1
	s_cbranch_vccnz .LBB0_418
	s_nop 0
	v_pk_mul_f32 v[158:159], v[70:71], v[118:119]
	v_pk_mul_f32 v[156:157], v[68:69], v[116:117]
	v_pk_mul_f32 v[168:169], v[66:67], v[114:115]
	v_pk_mul_f32 v[170:171], v[64:65], v[112:113]
	v_cvt_pk_bf16_f32 v156, v156, v157
	v_cvt_pk_bf16_f32 v157, v158, v159
	v_cvt_pk_bf16_f32 v158, v170, v171
	v_cvt_pk_bf16_f32 v159, v168, v169
	v_lshl_add_u64 v[152:153], v[152:153], 1, s[74:75]
	global_store_dwordx4 v[152:153], v[156:159], off sc1

.LBB0_420:
	s_or_b64 exec, exec, s[12:13]
	v_lshlrev_b32_e32 v114, 16, v164
	v_and_b32_e32 v115, 0xffff0000, v164
	v_lshlrev_b32_e32 v116, 16, v165
	v_and_b32_e32 v117, 0xffff0000, v165
	v_lshlrev_b32_e32 v118, 16, v166
	v_and_b32_e32 v119, 0xffff0000, v166
	v_lshlrev_b32_e32 v120, 16, v167
	v_and_b32_e32 v121, 0xffff0000, v167
	s_waitcnt lgkmcnt(0)
	v_lshlrev_b64 v[112:113], 10, v[212:213]
	v_pk_fma_f32 v[110:111], v[110:111], v[102:103], v[116:117]
	v_pk_fma_f32 v[108:109], v[108:109], v[100:101], v[114:115]
	v_pk_fma_f32 v[106:107], v[106:107], v[98:99], v[120:121]
	v_pk_fma_f32 v[104:105], v[104:105], v[96:97], v[118:119]
	v_lshl_add_u64 v[112:113], v[112:113], 0, v[204:205]
	v_cvt_pk_bf16_f32 v114, v108, v109
	v_cvt_pk_bf16_f32 v115, v110, v111
	v_cvt_pk_bf16_f32 v116, v104, v105
	v_cvt_pk_bf16_f32 v117, v106, v107
	s_and_b64 vcc, exec, s[40:41]
	global_store_dwordx4 v[214:215], v[114:117], off sc1
	s_cbranch_vccnz .LBB0_422
	s_nop 0
	v_pk_mul_f32 v[116:117], v[90:91], v[110:111]
	v_pk_mul_f32 v[114:115], v[88:89], v[108:109]
	v_pk_mul_f32 v[118:119], v[86:87], v[106:107]
	v_pk_mul_f32 v[120:121], v[84:85], v[104:105]
	v_cvt_pk_bf16_f32 v114, v114, v115
	v_cvt_pk_bf16_f32 v115, v116, v117
	v_cvt_pk_bf16_f32 v116, v120, v121
	v_cvt_pk_bf16_f32 v117, v118, v119
	v_lshl_add_u64 v[118:119], v[112:113], 1, s[74:75]
	global_store_dwordx4 v[118:119], v[114:117], off sc1
.LBB0_422:
	s_nop 1
	v_lshlrev_b32_e32 v114, 16, v160
	v_and_b32_e32 v115, 0xffff0000, v160
	v_lshlrev_b32_e32 v116, 16, v161
	v_and_b32_e32 v117, 0xffff0000, v161
	v_lshlrev_b32_e32 v118, 16, v162
	v_and_b32_e32 v119, 0xffff0000, v162
	v_lshlrev_b32_e32 v120, 16, v163
	v_and_b32_e32 v121, 0xffff0000, v163
	v_or_b32_e32 v112, 0x80, v112
	v_pk_fma_f32 v[94:95], v[94:95], v[78:79], v[116:117]
	v_pk_fma_f32 v[92:93], v[92:93], v[76:77], v[114:115]
	v_pk_fma_f32 v[82:83], v[82:83], v[74:75], v[120:121]
	v_pk_fma_f32 v[80:81], v[80:81], v[72:73], v[118:119]
	v_cvt_pk_bf16_f32 v114, v92, v93
	v_cvt_pk_bf16_f32 v115, v94, v95
	v_cvt_pk_bf16_f32 v116, v80, v81
	v_cvt_pk_bf16_f32 v117, v82, v83
	v_lshl_add_u64 v[118:119], v[112:113], 1, s[34:35]
	s_and_b64 vcc, exec, s[40:41]
	global_store_dwordx4 v[118:119], v[114:117], off sc1
	s_cbranch_vccnz .LBB0_424
	s_nop 0
	v_pk_mul_f32 v[116:117], v[70:71], v[94:95]
	v_pk_mul_f32 v[114:115], v[68:69], v[92:93]
	v_pk_mul_f32 v[118:119], v[66:67], v[82:83]
	v_pk_mul_f32 v[120:121], v[64:65], v[80:81]
	v_cvt_pk_bf16_f32 v114, v114, v115
	v_cvt_pk_bf16_f32 v115, v116, v117
	v_cvt_pk_bf16_f32 v116, v120, v121
	v_cvt_pk_bf16_f32 v117, v118, v119
	v_lshl_add_u64 v[112:113], v[112:113], 1, s[74:75]
	global_store_dwordx4 v[112:113], v[114:117], off sc1

.LBB0_426:
	s_or_b64 exec, exec, s[12:13]
	v_or_b32_e32 v80, 32, v148
	s_waitcnt lgkmcnt(0)
	v_ashrrev_i32_e32 v81, 31, v80
	v_lshlrev_b64 v[80:81], 11, v[80:81]
	v_add_u32_e32 v186, 0xb0, v206
	v_lshl_add_u64 v[80:81], v[210:211], 0, v[80:81]
	v_ashrrev_i32_e32 v187, 31, v186
	global_load_dwordx4 v[108:111], v[80:81], off nt
	global_load_dwordx4 v[104:107], v[80:81], off offset:256 nt
	v_lshlrev_b64 v[80:81], 11, v[186:187]
	v_lshl_add_u64 v[112:113], v[210:211], 0, v[80:81]
	global_load_dwordx4 v[92:95], v[112:113], off nt
	global_load_dwordx4 v[80:83], v[112:113], off offset:256 nt
	s_waitcnt vmcnt(11)
	v_lshlrev_b32_e32 v116, 16, v140
	v_and_b32_e32 v117, 0xffff0000, v140
	v_lshlrev_b32_e32 v118, 16, v141
	v_and_b32_e32 v119, 0xffff0000, v141
	v_lshlrev_b32_e32 v120, 16, v142
	v_and_b32_e32 v121, 0xffff0000, v142
	v_lshlrev_b32_e32 v122, 16, v143
	v_and_b32_e32 v123, 0xffff0000, v143
	v_lshlrev_b64 v[114:115], 10, v[148:149]
	v_pk_fma_f32 v[62:63], v[62:63], v[102:103], v[118:119]
	v_pk_fma_f32 v[60:61], v[60:61], v[100:101], v[116:117]
	v_pk_fma_f32 v[58:59], v[58:59], v[98:99], v[122:123]
	v_pk_fma_f32 v[56:57], v[56:57], v[96:97], v[120:121]
	v_lshl_add_u64 v[114:115], v[114:115], 0, v[204:205]
	v_cvt_pk_bf16_f32 v116, v60, v61
	v_cvt_pk_bf16_f32 v117, v62, v63
	v_cvt_pk_bf16_f32 v118, v56, v57
	v_cvt_pk_bf16_f32 v119, v58, v59
	s_and_b64 vcc, exec, s[40:41]
	global_store_dwordx4 v[150:151], v[116:119], off sc1
	s_cbranch_vccnz .LBB0_428
	s_nop 0
	v_pk_mul_f32 v[118:119], v[90:91], v[62:63]
	v_pk_mul_f32 v[116:117], v[88:89], v[60:61]
	v_pk_mul_f32 v[120:121], v[86:87], v[58:59]
	v_pk_mul_f32 v[122:123], v[84:85], v[56:57]
	v_cvt_pk_bf16_f32 v116, v116, v117
	v_cvt_pk_bf16_f32 v117, v118, v119
	v_cvt_pk_bf16_f32 v118, v122, v123
	v_cvt_pk_bf16_f32 v119, v120, v121
	v_lshl_add_u64 v[120:121], v[114:115], 1, s[74:75]
	global_store_dwordx4 v[120:121], v[116:119], off sc1
.LBB0_428:
	s_waitcnt vmcnt(11)
	s_nop 0
	v_lshlrev_b32_e32 v116, 16, v136
	v_and_b32_e32 v117, 0xffff0000, v136
	v_lshlrev_b32_e32 v118, 16, v137
	v_and_b32_e32 v119, 0xffff0000, v137
	v_lshlrev_b32_e32 v120, 16, v138
	v_and_b32_e32 v121, 0xffff0000, v138
	v_lshlrev_b32_e32 v122, 16, v139
	v_and_b32_e32 v123, 0xffff0000, v139
	v_or_b32_e32 v114, 0x80, v114
	v_pk_fma_f32 v[54:55], v[54:55], v[78:79], v[118:119]
	v_pk_fma_f32 v[52:53], v[52:53], v[76:77], v[116:117]
	v_pk_fma_f32 v[50:51], v[50:51], v[74:75], v[122:123]
	v_pk_fma_f32 v[48:49], v[48:49], v[72:73], v[120:121]
	v_cvt_pk_bf16_f32 v116, v52, v53
	v_cvt_pk_bf16_f32 v117, v54, v55
	v_cvt_pk_bf16_f32 v118, v48, v49
	v_cvt_pk_bf16_f32 v119, v50, v51
	v_lshl_add_u64 v[120:121], v[114:115], 1, s[34:35]
	s_and_b64 vcc, exec, s[40:41]
	global_store_dwordx4 v[120:121], v[116:119], off sc1
	s_cbranch_vccnz .LBB0_430
	s_nop 0
	v_pk_mul_f32 v[118:119], v[70:71], v[54:55]
	v_pk_mul_f32 v[116:117], v[68:69], v[52:53]
	v_pk_mul_f32 v[120:121], v[66:67], v[50:51]
	v_pk_mul_f32 v[122:123], v[64:65], v[48:49]
	v_cvt_pk_bf16_f32 v116, v116, v117
	v_cvt_pk_bf16_f32 v117, v118, v119
	v_cvt_pk_bf16_f32 v118, v122, v123
	v_cvt_pk_bf16_f32 v119, v120, v121
	v_lshl_add_u64 v[114:115], v[114:115], 1, s[74:75]
	global_store_dwordx4 v[114:115], v[116:119], off sc1

.LBB0_432:
	s_or_b64 exec, exec, s[12:13]
	s_waitcnt vmcnt(11)
	v_lshlrev_b32_e32 v50, 16, v132
	v_and_b32_e32 v51, 0xffff0000, v132
	v_lshlrev_b32_e32 v52, 16, v133
	v_and_b32_e32 v53, 0xffff0000, v133
	v_lshlrev_b32_e32 v54, 16, v134
	v_and_b32_e32 v55, 0xffff0000, v134
	v_lshlrev_b32_e32 v56, 16, v135
	v_and_b32_e32 v57, 0xffff0000, v135
	s_waitcnt lgkmcnt(0)
	v_lshlrev_b64 v[48:49], 10, v[144:145]
	v_pk_fma_f32 v[46:47], v[46:47], v[102:103], v[52:53]
	v_pk_fma_f32 v[44:45], v[44:45], v[100:101], v[50:51]
	v_pk_fma_f32 v[42:43], v[42:43], v[98:99], v[56:57]
	v_pk_fma_f32 v[40:41], v[40:41], v[96:97], v[54:55]
	v_lshl_add_u64 v[48:49], v[48:49], 0, v[204:205]
	v_cvt_pk_bf16_f32 v50, v44, v45
	v_cvt_pk_bf16_f32 v51, v46, v47
	v_cvt_pk_bf16_f32 v52, v40, v41
	v_cvt_pk_bf16_f32 v53, v42, v43
	s_and_b64 vcc, exec, s[40:41]
	global_store_dwordx4 v[146:147], v[50:53], off sc1
	s_cbranch_vccnz .LBB0_434
	s_nop 0
	v_pk_mul_f32 v[52:53], v[90:91], v[46:47]
	v_pk_mul_f32 v[50:51], v[88:89], v[44:45]
	v_pk_mul_f32 v[54:55], v[86:87], v[42:43]
	v_pk_mul_f32 v[56:57], v[84:85], v[40:41]
	v_cvt_pk_bf16_f32 v50, v50, v51
	v_cvt_pk_bf16_f32 v51, v52, v53
	v_cvt_pk_bf16_f32 v52, v56, v57
	v_cvt_pk_bf16_f32 v53, v54, v55
	v_lshl_add_u64 v[54:55], v[48:49], 1, s[74:75]
	global_store_dwordx4 v[54:55], v[50:53], off sc1
.LBB0_434:
	s_waitcnt vmcnt(11)
	s_nop 0
	v_lshlrev_b32_e32 v50, 16, v128
	v_and_b32_e32 v51, 0xffff0000, v128
	v_lshlrev_b32_e32 v52, 16, v129
	v_and_b32_e32 v53, 0xffff0000, v129
	v_lshlrev_b32_e32 v54, 16, v130
	v_and_b32_e32 v55, 0xffff0000, v130
	v_lshlrev_b32_e32 v56, 16, v131
	v_and_b32_e32 v57, 0xffff0000, v131
	v_or_b32_e32 v48, 0x80, v48
	v_pk_fma_f32 v[38:39], v[38:39], v[78:79], v[52:53]
	v_pk_fma_f32 v[36:37], v[36:37], v[76:77], v[50:51]
	v_pk_fma_f32 v[34:35], v[34:35], v[74:75], v[56:57]
	v_pk_fma_f32 v[32:33], v[32:33], v[72:73], v[54:55]
	v_cvt_pk_bf16_f32 v50, v36, v37
	v_cvt_pk_bf16_f32 v51, v38, v39
	v_cvt_pk_bf16_f32 v52, v32, v33
	v_cvt_pk_bf16_f32 v53, v34, v35
	v_lshl_add_u64 v[54:55], v[48:49], 1, s[34:35]
	s_and_b64 vcc, exec, s[40:41]
	global_store_dwordx4 v[54:55], v[50:53], off sc1
	s_cbranch_vccnz .LBB0_436
	s_nop 0
	v_pk_mul_f32 v[52:53], v[70:71], v[38:39]
	v_pk_mul_f32 v[50:51], v[68:69], v[36:37]
	v_pk_mul_f32 v[54:55], v[66:67], v[34:35]
	v_pk_mul_f32 v[56:57], v[64:65], v[32:33]
	v_cvt_pk_bf16_f32 v50, v50, v51
	v_cvt_pk_bf16_f32 v51, v52, v53
	v_cvt_pk_bf16_f32 v52, v56, v57
	v_cvt_pk_bf16_f32 v53, v54, v55
	v_lshl_add_u64 v[48:49], v[48:49], 1, s[74:75]
	global_store_dwordx4 v[48:49], v[50:53], off sc1

.LBB0_438:
	s_or_b64 exec, exec, s[12:13]
	v_add_u32_e32 v32, 0xa0, v206
	s_waitcnt vmcnt(7)
	v_lshlrev_b32_e32 v36, 16, v108
	v_and_b32_e32 v37, 0xffff0000, v108
	v_lshlrev_b32_e32 v38, 16, v109
	v_and_b32_e32 v39, 0xffff0000, v109
	v_lshlrev_b32_e32 v40, 16, v110
	v_and_b32_e32 v41, 0xffff0000, v110
	v_lshlrev_b32_e32 v42, 16, v111
	v_and_b32_e32 v43, 0xffff0000, v111
	s_waitcnt lgkmcnt(0)
	v_ashrrev_i32_e32 v33, 31, v32
	v_lshlrev_b64 v[34:35], 10, v[32:33]
	v_pk_fma_f32 v[30:31], v[30:31], v[102:103], v[38:39]
	v_pk_fma_f32 v[28:29], v[28:29], v[100:101], v[36:37]
	v_pk_fma_f32 v[26:27], v[26:27], v[98:99], v[42:43]
	v_pk_fma_f32 v[24:25], v[24:25], v[96:97], v[40:41]
	v_lshlrev_b64 v[40:41], 11, v[32:33]
	v_lshl_add_u64 v[34:35], v[34:35], 0, v[204:205]
	v_cvt_pk_bf16_f32 v36, v28, v29
	v_cvt_pk_bf16_f32 v37, v30, v31
	v_cvt_pk_bf16_f32 v38, v24, v25
	v_cvt_pk_bf16_f32 v39, v26, v27
	v_lshl_add_u64 v[40:41], v[210:211], 0, v[40:41]
	s_and_b64 vcc, exec, s[40:41]
	global_store_dwordx4 v[40:41], v[36:39], off sc1
	s_cbranch_vccnz .LBB0_440
	s_nop 0
	v_pk_mul_f32 v[38:39], v[90:91], v[30:31]
	v_pk_mul_f32 v[36:37], v[88:89], v[28:29]
	v_pk_mul_f32 v[40:41], v[86:87], v[26:27]
	v_pk_mul_f32 v[42:43], v[84:85], v[24:25]
	v_cvt_pk_bf16_f32 v36, v36, v37
	v_cvt_pk_bf16_f32 v37, v38, v39
	v_cvt_pk_bf16_f32 v38, v42, v43
	v_cvt_pk_bf16_f32 v39, v40, v41
	v_lshl_add_u64 v[40:41], v[34:35], 1, s[74:75]
	global_store_dwordx4 v[40:41], v[36:39], off sc1
.LBB0_440:
	s_waitcnt vmcnt(7)
	s_nop 0
	v_lshlrev_b32_e32 v36, 16, v104
	v_and_b32_e32 v37, 0xffff0000, v104
	v_lshlrev_b32_e32 v38, 16, v105
	v_and_b32_e32 v39, 0xffff0000, v105
	v_lshlrev_b32_e32 v40, 16, v106
	v_and_b32_e32 v41, 0xffff0000, v106
	v_lshlrev_b32_e32 v42, 16, v107
	v_and_b32_e32 v43, 0xffff0000, v107
	v_or_b32_e32 v34, 0x80, v34
	v_pk_fma_f32 v[22:23], v[22:23], v[78:79], v[38:39]
	v_pk_fma_f32 v[20:21], v[20:21], v[76:77], v[36:37]
	v_pk_fma_f32 v[18:19], v[18:19], v[74:75], v[42:43]
	v_pk_fma_f32 v[16:17], v[16:17], v[72:73], v[40:41]
	v_cvt_pk_bf16_f32 v36, v20, v21
	v_cvt_pk_bf16_f32 v37, v22, v23
	v_cvt_pk_bf16_f32 v38, v16, v17
	v_cvt_pk_bf16_f32 v39, v18, v19
	v_lshl_add_u64 v[40:41], v[34:35], 1, s[34:35]
	s_and_b64 vcc, exec, s[40:41]
	global_store_dwordx4 v[40:41], v[36:39], off sc1
	s_cbranch_vccnz .LBB0_442
	s_nop 0
	v_pk_mul_f32 v[38:39], v[70:71], v[22:23]
	v_pk_mul_f32 v[36:37], v[68:69], v[20:21]
	v_pk_mul_f32 v[40:41], v[66:67], v[18:19]
	v_pk_mul_f32 v[42:43], v[64:65], v[16:17]
	v_cvt_pk_bf16_f32 v36, v36, v37
	v_cvt_pk_bf16_f32 v37, v38, v39
	v_cvt_pk_bf16_f32 v38, v42, v43
	v_cvt_pk_bf16_f32 v39, v40, v41
	v_lshl_add_u64 v[34:35], v[34:35], 1, s[74:75]
	global_store_dwordx4 v[34:35], v[36:39], off sc1

.LBB0_444:
	s_or_b64 exec, exec, s[12:13]
	s_waitcnt vmcnt(7)
	v_lshlrev_b32_e32 v18, 16, v92
	v_and_b32_e32 v19, 0xffff0000, v92
	v_lshlrev_b32_e32 v20, 16, v93
	v_and_b32_e32 v21, 0xffff0000, v93
	v_lshlrev_b32_e32 v22, 16, v94
	v_and_b32_e32 v23, 0xffff0000, v94
	v_lshlrev_b32_e32 v24, 16, v95
	v_and_b32_e32 v25, 0xffff0000, v95
	s_waitcnt lgkmcnt(0)
	v_lshlrev_b64 v[16:17], 10, v[186:187]
	v_pk_fma_f32 v[14:15], v[14:15], v[102:103], v[20:21]
	v_pk_fma_f32 v[12:13], v[12:13], v[100:101], v[18:19]
	v_pk_fma_f32 v[10:11], v[10:11], v[98:99], v[24:25]
	v_pk_fma_f32 v[8:9], v[8:9], v[96:97], v[22:23]
	v_lshl_add_u64 v[16:17], v[16:17], 0, v[204:205]
	v_cvt_pk_bf16_f32 v18, v12, v13
	v_cvt_pk_bf16_f32 v19, v14, v15
	v_cvt_pk_bf16_f32 v20, v8, v9
	v_cvt_pk_bf16_f32 v21, v10, v11
	s_and_b64 vcc, exec, s[40:41]
	global_store_dwordx4 v[112:113], v[18:21], off sc1
	s_cbranch_vccnz .LBB0_446
	s_nop 0
	v_pk_mul_f32 v[20:21], v[90:91], v[14:15]
	v_pk_mul_f32 v[18:19], v[88:89], v[12:13]
	v_pk_mul_f32 v[22:23], v[86:87], v[10:11]
	v_pk_mul_f32 v[24:25], v[84:85], v[8:9]
	v_cvt_pk_bf16_f32 v18, v18, v19
	v_cvt_pk_bf16_f32 v19, v20, v21
	v_cvt_pk_bf16_f32 v20, v24, v25
	v_cvt_pk_bf16_f32 v21, v22, v23
	v_lshl_add_u64 v[22:23], v[16:17], 1, s[74:75]
	global_store_dwordx4 v[22:23], v[18:21], off sc1
.LBB0_446:
	s_waitcnt vmcnt(7)
	s_nop 0
	v_lshlrev_b32_e32 v18, 16, v80
	v_and_b32_e32 v19, 0xffff0000, v80
	v_lshlrev_b32_e32 v20, 16, v81
	v_and_b32_e32 v21, 0xffff0000, v81
	v_lshlrev_b32_e32 v22, 16, v82
	v_and_b32_e32 v23, 0xffff0000, v82
	v_lshlrev_b32_e32 v24, 16, v83
	v_and_b32_e32 v25, 0xffff0000, v83
	v_or_b32_e32 v16, 0x80, v16
	v_pk_fma_f32 v[6:7], v[6:7], v[78:79], v[20:21]
	v_pk_fma_f32 v[4:5], v[4:5], v[76:77], v[18:19]
	v_pk_fma_f32 v[2:3], v[2:3], v[74:75], v[24:25]
	v_pk_fma_f32 v[0:1], v[0:1], v[72:73], v[22:23]
	v_cvt_pk_bf16_f32 v18, v4, v5
	v_cvt_pk_bf16_f32 v19, v6, v7
	v_cvt_pk_bf16_f32 v20, v0, v1
	v_cvt_pk_bf16_f32 v21, v2, v3
	v_lshl_add_u64 v[22:23], v[16:17], 1, s[34:35]
	s_and_b64 vcc, exec, s[40:41]
	global_store_dwordx4 v[22:23], v[18:21], off sc1
	s_cbranch_vccnz .LBB0_448
	s_nop 0
	v_pk_mul_f32 v[20:21], v[70:71], v[6:7]
	v_pk_mul_f32 v[18:19], v[68:69], v[4:5]
	v_pk_mul_f32 v[22:23], v[66:67], v[2:3]
	v_pk_mul_f32 v[24:25], v[64:65], v[0:1]
	v_cvt_pk_bf16_f32 v18, v18, v19
	v_cvt_pk_bf16_f32 v19, v20, v21
	v_cvt_pk_bf16_f32 v20, v24, v25
	v_cvt_pk_bf16_f32 v21, v22, v23
	v_lshl_add_u64 v[16:17], v[16:17], 1, s[74:75]
	global_store_dwordx4 v[16:17], v[18:21], off sc1

.LBB0_511:
	s_cmp_lg_u32 s84, 0
	v_lshl_add_u32 v162, s38, 8, v153
	s_cbranch_scc0 .LBB0_578
	s_ashr_i32 s12, s48, 3
	s_ashr_i32 s13, s12, 31
	s_sub_i32 s33, s36, s37
	s_lshl_b64 s[12:13], s[12:13], 12
	s_lshl_b32 s22, s33, 10
	s_lshl_b64 s[12:13], s[12:13], s72
	s_add_u32 s12, s10, s12
	s_addc_u32 s13, s11, s13
	s_lshl_b32 s23, s48, 9
	v_add_u32_e32 v132, s22, v203
	v_add_u32_e32 v173, s22, v157
	s_and_b32 s23, s23, 0xe00
	ds_read_b128 v[128:131], v132 offset:16
	ds_read_b128 v[132:135], v132
	ds_read_b32 v172, v173
	s_add_u32 s12, s12, s23
	s_addc_u32 s13, s13, 0
	s_add_u32 s12, s12, s81
	v_ashrrev_i32_e32 v163, 31, v162
	s_addc_u32 s13, s13, 0
	v_lshlrev_b64 v[136:137], 12, v[162:163]
	v_lshl_add_u64 v[164:165], s[12:13], 0, v[136:137]
	s_waitcnt lgkmcnt(0)
	v_pk_fma_f32 v[136:137], v[124:125], v[132:133], v[172:173] op_sel_hi:[1,1,0]
	v_pk_fma_f32 v[138:139], v[126:127], v[134:135], v[172:173] op_sel_hi:[1,1,0]
	v_cvt_pk_bf16_f32 v136, v136, v137
	v_cvt_pk_bf16_f32 v137, v138, v139
	v_pk_fma_f32 v[138:139], v[120:121], v[128:129], v[172:173] op_sel_hi:[1,1,0]
	v_pk_fma_f32 v[140:141], v[122:123], v[130:131], v[172:173] op_sel_hi:[1,1,0]
	v_cvt_pk_bf16_f32 v138, v138, v139
	v_cvt_pk_bf16_f32 v139, v140, v141
	s_mov_b64 s[22:23], -1
	s_and_b64 vcc, exec, s[2:3]
	v_lshlrev_b32_e32 v140, 1, v152
	s_cbranch_vccz .LBB0_514
	v_mov_b32_e32 v141, v189
	v_lshl_add_u64 v[142:143], v[164:165], 0, v[140:141]
	global_store_dwordx4 v[142:143], v[136:139], off sc1
	s_mov_b64 s[22:23], 0

.LBB0_516:
	ds_read_b32 v176, v173 offset:64
	v_or_b32_e32 v136, 16, v162
	v_ashrrev_i32_e32 v137, 31, v136
	v_lshlrev_b64 v[136:137], 12, v[136:137]
	v_lshl_add_u64 v[166:167], s[12:13], 0, v[136:137]
	s_waitcnt lgkmcnt(0)
	v_pk_fma_f32 v[136:137], v[108:109], v[132:133], v[176:177] op_sel_hi:[1,1,0]
	v_pk_fma_f32 v[138:139], v[110:111], v[134:135], v[176:177] op_sel_hi:[1,1,0]
	v_cvt_pk_bf16_f32 v136, v136, v137
	v_cvt_pk_bf16_f32 v137, v138, v139
	v_pk_fma_f32 v[138:139], v[104:105], v[128:129], v[176:177] op_sel_hi:[1,1,0]
	v_pk_fma_f32 v[168:169], v[106:107], v[130:131], v[176:177] op_sel_hi:[1,1,0]
	v_cvt_pk_bf16_f32 v138, v138, v139
	v_cvt_pk_bf16_f32 v139, v168, v169
	s_mov_b64 s[22:23], -1
	s_and_b64 vcc, exec, s[2:3]
	s_cbranch_vccz .LBB0_518
	v_mov_b32_e32 v141, v189
	v_lshl_add_u64 v[168:169], v[166:167], 0, v[140:141]
	global_store_dwordx4 v[168:169], v[136:139], off sc1
	s_mov_b64 s[22:23], 0

.LBB0_520:
	ds_read_b32 v180, v173 offset:128
	v_or_b32_e32 v136, 32, v162
	v_ashrrev_i32_e32 v137, 31, v136
	v_lshlrev_b64 v[136:137], 12, v[136:137]
	v_lshl_add_u64 v[168:169], s[12:13], 0, v[136:137]
	s_waitcnt lgkmcnt(0)
	v_pk_fma_f32 v[136:137], v[92:93], v[132:133], v[180:181] op_sel_hi:[1,1,0]
	v_pk_fma_f32 v[138:139], v[94:95], v[134:135], v[180:181] op_sel_hi:[1,1,0]
	v_cvt_pk_bf16_f32 v136, v136, v137
	v_cvt_pk_bf16_f32 v137, v138, v139
	v_pk_fma_f32 v[138:139], v[88:89], v[128:129], v[180:181] op_sel_hi:[1,1,0]
	v_pk_fma_f32 v[170:171], v[90:91], v[130:131], v[180:181] op_sel_hi:[1,1,0]
	v_cvt_pk_bf16_f32 v138, v138, v139
	v_cvt_pk_bf16_f32 v139, v170, v171
	s_mov_b64 s[22:23], -1
	s_and_b64 vcc, exec, s[2:3]
	s_cbranch_vccz .LBB0_522
	v_mov_b32_e32 v141, v189
	v_lshl_add_u64 v[170:171], v[168:169], 0, v[140:141]
	global_store_dwordx4 v[170:171], v[136:139], off sc1
	s_mov_b64 s[22:23], 0

.LBB0_524:
	ds_read_b32 v182, v173 offset:192
	v_or_b32_e32 v136, 48, v162
	v_ashrrev_i32_e32 v137, 31, v136
	v_lshlrev_b64 v[136:137], 12, v[136:137]
	v_lshl_add_u64 v[170:171], s[12:13], 0, v[136:137]
	s_waitcnt lgkmcnt(0)
	v_pk_fma_f32 v[136:137], v[76:77], v[132:133], v[182:183] op_sel_hi:[1,1,0]
	v_pk_fma_f32 v[138:139], v[78:79], v[134:135], v[182:183] op_sel_hi:[1,1,0]
	v_cvt_pk_bf16_f32 v136, v136, v137
	v_cvt_pk_bf16_f32 v137, v138, v139
	v_pk_fma_f32 v[138:139], v[72:73], v[128:129], v[182:183] op_sel_hi:[1,1,0]
	v_pk_fma_f32 v[174:175], v[74:75], v[130:131], v[182:183] op_sel_hi:[1,1,0]
	v_cvt_pk_bf16_f32 v138, v138, v139
	v_cvt_pk_bf16_f32 v139, v174, v175
	s_mov_b64 s[22:23], -1
	s_and_b64 vcc, exec, s[2:3]
	s_cbranch_vccz .LBB0_526
	v_mov_b32_e32 v141, v189
	v_lshl_add_u64 v[174:175], v[170:171], 0, v[140:141]
	global_store_dwordx4 v[174:175], v[136:139], off sc1
	s_mov_b64 s[22:23], 0

.LBB0_528:
	ds_read_b32 v186, v173 offset:512
	v_lshlrev_b64 v[136:137], 12, v[162:163]
	v_lshl_add_u64 v[136:137], s[12:13], 0, v[136:137]
	s_mov_b64 s[22:23], 0x80000
	v_lshl_add_u64 v[174:175], v[136:137], 0, s[22:23]
	s_waitcnt lgkmcnt(0)
	v_pk_fma_f32 v[136:137], v[60:61], v[132:133], v[186:187] op_sel_hi:[1,1,0]
	v_pk_fma_f32 v[138:139], v[62:63], v[134:135], v[186:187] op_sel_hi:[1,1,0]
	v_cvt_pk_bf16_f32 v136, v136, v137
	v_cvt_pk_bf16_f32 v137, v138, v139
	v_pk_fma_f32 v[138:139], v[56:57], v[128:129], v[186:187] op_sel_hi:[1,1,0]
	v_pk_fma_f32 v[178:179], v[58:59], v[130:131], v[186:187] op_sel_hi:[1,1,0]
	v_cvt_pk_bf16_f32 v138, v138, v139
	v_cvt_pk_bf16_f32 v139, v178, v179
	s_mov_b64 s[22:23], -1
	s_and_b64 vcc, exec, s[2:3]
	s_cbranch_vccz .LBB0_530
	v_mov_b32_e32 v141, v189
	v_lshl_add_u64 v[178:179], v[174:175], 0, v[140:141]
	global_store_dwordx4 v[178:179], v[136:139], off sc1
	s_mov_b64 s[22:23], 0

.LBB0_532:
	ds_read_b32 v196, v173 offset:576
	v_lshlrev_b64 v[136:137], 12, v[162:163]
	v_lshl_add_u64 v[136:137], s[12:13], 0, v[136:137]
	s_mov_b64 s[22:23], 0x90000
	v_lshl_add_u64 v[178:179], v[136:137], 0, s[22:23]
	s_waitcnt lgkmcnt(0)
	v_pk_fma_f32 v[136:137], v[44:45], v[132:133], v[196:197] op_sel_hi:[1,1,0]
	v_pk_fma_f32 v[138:139], v[46:47], v[134:135], v[196:197] op_sel_hi:[1,1,0]
	v_cvt_pk_bf16_f32 v136, v136, v137
	v_cvt_pk_bf16_f32 v137, v138, v139
	v_pk_fma_f32 v[138:139], v[40:41], v[128:129], v[196:197] op_sel_hi:[1,1,0]
	v_pk_fma_f32 v[184:185], v[42:43], v[130:131], v[196:197] op_sel_hi:[1,1,0]
	v_cvt_pk_bf16_f32 v138, v138, v139
	v_cvt_pk_bf16_f32 v139, v184, v185
	s_mov_b64 s[22:23], -1
	s_and_b64 vcc, exec, s[2:3]
	s_cbranch_vccz .LBB0_534
	v_mov_b32_e32 v141, v189
	v_lshl_add_u64 v[184:185], v[178:179], 0, v[140:141]
	global_store_dwordx4 v[184:185], v[136:139], off sc1
	s_mov_b64 s[22:23], 0

.LBB0_536:
	ds_read_b32 v198, v173 offset:640
	v_lshlrev_b64 v[136:137], 12, v[162:163]
	v_lshl_add_u64 v[136:137], s[12:13], 0, v[136:137]
	s_mov_b64 s[22:23], 0xa0000
	v_lshl_add_u64 v[184:185], v[136:137], 0, s[22:23]
	s_waitcnt lgkmcnt(0)
	v_pk_fma_f32 v[136:137], v[28:29], v[132:133], v[198:199] op_sel_hi:[1,1,0]
	v_pk_fma_f32 v[138:139], v[30:31], v[134:135], v[198:199] op_sel_hi:[1,1,0]
	v_cvt_pk_bf16_f32 v136, v136, v137
	v_cvt_pk_bf16_f32 v137, v138, v139
	v_pk_fma_f32 v[138:139], v[24:25], v[128:129], v[198:199] op_sel_hi:[1,1,0]
	v_pk_fma_f32 v[194:195], v[26:27], v[130:131], v[198:199] op_sel_hi:[1,1,0]
	v_cvt_pk_bf16_f32 v138, v138, v139
	v_cvt_pk_bf16_f32 v139, v194, v195
	s_mov_b64 s[22:23], -1
	s_and_b64 vcc, exec, s[2:3]
	s_cbranch_vccz .LBB0_538
	v_mov_b32_e32 v141, v189
	v_lshl_add_u64 v[194:195], v[184:185], 0, v[140:141]
	global_store_dwordx4 v[194:195], v[136:139], off sc1
	s_mov_b64 s[22:23], 0

.LBB0_540:
	ds_read_b32 v200, v173 offset:704
	v_lshlrev_b64 v[136:137], 12, v[162:163]
	v_lshl_add_u64 v[136:137], s[12:13], 0, v[136:137]
	s_mov_b64 s[12:13], 0xb0000
	v_lshl_add_u64 v[194:195], v[136:137], 0, s[12:13]
	s_waitcnt lgkmcnt(0)
	v_pk_fma_f32 v[132:133], v[12:13], v[132:133], v[200:201] op_sel_hi:[1,1,0]
	v_pk_fma_f32 v[134:135], v[14:15], v[134:135], v[200:201] op_sel_hi:[1,1,0]
	v_pk_fma_f32 v[128:129], v[8:9], v[128:129], v[200:201] op_sel_hi:[1,1,0]
	v_cvt_pk_bf16_f32 v132, v132, v133
	v_cvt_pk_bf16_f32 v133, v134, v135
	v_cvt_pk_bf16_f32 v134, v128, v129
	v_pk_fma_f32 v[128:129], v[10:11], v[130:131], v[200:201] op_sel_hi:[1,1,0]
	s_mov_b64 s[12:13], -1
	v_cvt_pk_bf16_f32 v135, v128, v129
	s_and_b64 vcc, exec, s[2:3]
	s_cbranch_vccz .LBB0_542
	v_mov_b32_e32 v141, v189
	v_lshl_add_u64 v[128:129], v[194:195], 0, v[140:141]
	global_store_dwordx4 v[128:129], v[132:135], off sc1
	s_mov_b64 s[12:13], 0

.LBB0_544:
	s_lshl_b32 s12, s33, 8
	v_lshl_add_u32 v128, s12, 2, v204
	ds_read_b128 v[132:135], v128
	ds_read_b128 v[128:131], v128 offset:16
	v_mov_b32_e32 v173, v172
	s_mov_b64 s[12:13], -1
	s_and_b64 vcc, exec, s[2:3]
	s_waitcnt lgkmcnt(0)
	v_pk_fma_f32 v[136:137], v[116:117], v[132:133], v[172:173]
	v_pk_fma_f32 v[138:139], v[118:119], v[134:135], v[172:173]
	v_cvt_pk_bf16_f32 v136, v136, v137
	v_cvt_pk_bf16_f32 v137, v138, v139
	v_pk_fma_f32 v[138:139], v[112:113], v[128:129], v[172:173]
	v_pk_fma_f32 v[172:173], v[114:115], v[130:131], v[172:173]
	v_cvt_pk_bf16_f32 v138, v138, v139
	v_cvt_pk_bf16_f32 v139, v172, v173
	s_cbranch_vccz .LBB0_546
	v_mov_b32_e32 v141, v189
	v_lshl_add_u64 v[172:173], v[164:165], 0, v[140:141]
	global_store_dwordx4 v[172:173], v[136:139], off offset:256 sc1
	s_mov_b64 s[12:13], 0

.LBB0_548:
	v_mov_b32_e32 v177, v176
	v_pk_fma_f32 v[136:137], v[100:101], v[132:133], v[176:177]
	v_pk_fma_f32 v[138:139], v[102:103], v[134:135], v[176:177]
	v_cvt_pk_bf16_f32 v136, v136, v137
	v_cvt_pk_bf16_f32 v137, v138, v139
	v_pk_fma_f32 v[138:139], v[96:97], v[128:129], v[176:177]
	v_pk_fma_f32 v[164:165], v[98:99], v[130:131], v[176:177]
	v_cvt_pk_bf16_f32 v138, v138, v139
	v_cvt_pk_bf16_f32 v139, v164, v165
	s_mov_b64 s[12:13], -1
	s_and_b64 vcc, exec, s[2:3]
	s_cbranch_vccz .LBB0_550
	v_mov_b32_e32 v141, v189
	v_lshl_add_u64 v[164:165], v[166:167], 0, v[140:141]
	global_store_dwordx4 v[164:165], v[136:139], off offset:256 sc1
	s_mov_b64 s[12:13], 0

.LBB0_552:
	v_mov_b32_e32 v181, v180
	v_pk_fma_f32 v[136:137], v[84:85], v[132:133], v[180:181]
	v_pk_fma_f32 v[138:139], v[86:87], v[134:135], v[180:181]
	v_cvt_pk_bf16_f32 v136, v136, v137
	v_cvt_pk_bf16_f32 v137, v138, v139
	v_pk_fma_f32 v[138:139], v[80:81], v[128:129], v[180:181]
	v_pk_fma_f32 v[164:165], v[82:83], v[130:131], v[180:181]
	v_cvt_pk_bf16_f32 v138, v138, v139
	v_cvt_pk_bf16_f32 v139, v164, v165
	s_mov_b64 s[12:13], -1
	s_and_b64 vcc, exec, s[2:3]
	s_cbranch_vccz .LBB0_554
	v_mov_b32_e32 v141, v189
	v_lshl_add_u64 v[164:165], v[168:169], 0, v[140:141]
	global_store_dwordx4 v[164:165], v[136:139], off offset:256 sc1
	s_mov_b64 s[12:13], 0

.LBB0_556:
	v_mov_b32_e32 v183, v182
	v_pk_fma_f32 v[136:137], v[68:69], v[132:133], v[182:183]
	v_pk_fma_f32 v[138:139], v[70:71], v[134:135], v[182:183]
	v_cvt_pk_bf16_f32 v136, v136, v137
	v_cvt_pk_bf16_f32 v137, v138, v139
	v_pk_fma_f32 v[138:139], v[64:65], v[128:129], v[182:183]
	v_pk_fma_f32 v[164:165], v[66:67], v[130:131], v[182:183]
	v_cvt_pk_bf16_f32 v138, v138, v139
	v_cvt_pk_bf16_f32 v139, v164, v165
	s_mov_b64 s[12:13], -1
	s_and_b64 vcc, exec, s[2:3]
	s_cbranch_vccz .LBB0_558
	v_mov_b32_e32 v141, v189
	v_lshl_add_u64 v[164:165], v[170:171], 0, v[140:141]
	global_store_dwordx4 v[164:165], v[136:139], off offset:256 sc1
	s_mov_b64 s[12:13], 0

.LBB0_560:
	v_mov_b32_e32 v187, v186
	v_pk_fma_f32 v[136:137], v[52:53], v[132:133], v[186:187]
	v_pk_fma_f32 v[138:139], v[54:55], v[134:135], v[186:187]
	v_cvt_pk_bf16_f32 v136, v136, v137
	v_cvt_pk_bf16_f32 v137, v138, v139
	v_pk_fma_f32 v[138:139], v[48:49], v[128:129], v[186:187]
	v_pk_fma_f32 v[164:165], v[50:51], v[130:131], v[186:187]
	v_cvt_pk_bf16_f32 v138, v138, v139
	v_cvt_pk_bf16_f32 v139, v164, v165
	s_mov_b64 s[12:13], -1
	s_and_b64 vcc, exec, s[2:3]
	s_cbranch_vccz .LBB0_562
	v_mov_b32_e32 v141, v189
	v_lshl_add_u64 v[164:165], v[174:175], 0, v[140:141]
	global_store_dwordx4 v[164:165], v[136:139], off offset:256 sc1
	s_mov_b64 s[12:13], 0

.LBB0_564:
	v_mov_b32_e32 v197, v196
	v_pk_fma_f32 v[136:137], v[36:37], v[132:133], v[196:197]
	v_pk_fma_f32 v[138:139], v[38:39], v[134:135], v[196:197]
	v_cvt_pk_bf16_f32 v136, v136, v137
	v_cvt_pk_bf16_f32 v137, v138, v139
	v_pk_fma_f32 v[138:139], v[32:33], v[128:129], v[196:197]
	v_pk_fma_f32 v[164:165], v[34:35], v[130:131], v[196:197]
	v_cvt_pk_bf16_f32 v138, v138, v139
	v_cvt_pk_bf16_f32 v139, v164, v165
	s_mov_b64 s[12:13], -1
	s_and_b64 vcc, exec, s[2:3]
	s_cbranch_vccz .LBB0_566
	v_mov_b32_e32 v141, v189
	v_lshl_add_u64 v[164:165], v[178:179], 0, v[140:141]
	global_store_dwordx4 v[164:165], v[136:139], off offset:256 sc1
	s_mov_b64 s[12:13], 0

.LBB0_568:
	v_mov_b32_e32 v199, v198
	v_pk_fma_f32 v[136:137], v[20:21], v[132:133], v[198:199]
	v_pk_fma_f32 v[138:139], v[22:23], v[134:135], v[198:199]
	v_cvt_pk_bf16_f32 v136, v136, v137
	v_cvt_pk_bf16_f32 v137, v138, v139
	v_pk_fma_f32 v[138:139], v[16:17], v[128:129], v[198:199]
	v_pk_fma_f32 v[164:165], v[18:19], v[130:131], v[198:199]
	v_cvt_pk_bf16_f32 v138, v138, v139
	v_cvt_pk_bf16_f32 v139, v164, v165
	s_mov_b64 s[12:13], -1
	s_and_b64 vcc, exec, s[2:3]
	s_cbranch_vccz .LBB0_570
	v_mov_b32_e32 v141, v189
	v_lshl_add_u64 v[164:165], v[184:185], 0, v[140:141]
	global_store_dwordx4 v[164:165], v[136:139], off offset:256 sc1
	s_mov_b64 s[12:13], 0

.LBB0_572:
	v_mov_b32_e32 v201, v200
	v_pk_fma_f32 v[132:133], v[4:5], v[132:133], v[200:201]
	v_pk_fma_f32 v[134:135], v[6:7], v[134:135], v[200:201]
	v_pk_fma_f32 v[128:129], v[0:1], v[128:129], v[200:201]
	v_cvt_pk_bf16_f32 v132, v132, v133
	v_cvt_pk_bf16_f32 v133, v134, v135
	v_cvt_pk_bf16_f32 v134, v128, v129
	v_pk_fma_f32 v[128:129], v[2:3], v[130:131], v[200:201]
	s_mov_b64 s[12:13], -1
	v_cvt_pk_bf16_f32 v135, v128, v129
	s_and_b64 vcc, exec, s[2:3]
	s_cbranch_vccz .LBB0_574
	v_mov_b32_e32 v141, v189
	v_lshl_add_u64 v[128:129], v[194:195], 0, v[140:141]
	global_store_dwordx4 v[128:129], v[132:135], off offset:256 sc1
	s_mov_b64 s[12:13], 0

.LBB0_583:
	s_cmp_lt_i32 s39, s53
	s_cselect_b64 vcc, -1, 0
	v_mov_b32_e32 v165, 0x3e38aa3b
	v_cndmask_b32_e32 v168, 1.0, v165, vcc
	s_waitcnt lgkmcnt(0)
	v_pk_fma_f32 v[126:127], v[126:127], v[170:171], v[142:143] op_sel_hi:[1,0,1]
	v_pk_fma_f32 v[124:125], v[124:125], v[170:171], v[140:141] op_sel_hi:[1,0,1]
	v_pk_fma_f32 v[122:123], v[122:123], v[170:171], v[138:139] op_sel_hi:[1,0,1]
	v_pk_fma_f32 v[120:121], v[120:121], v[170:171], v[136:137] op_sel_hi:[1,0,1]
	s_bitset1_b32 s39, 7
	v_pk_mul_f32 v[126:127], v[168:169], v[126:127] op_sel_hi:[0,1]
	v_pk_mul_f32 v[124:125], v[168:169], v[124:125] op_sel_hi:[0,1]
	v_pk_mul_f32 v[174:175], v[168:169], v[122:123] op_sel_hi:[0,1]
	v_pk_mul_f32 v[122:123], v[168:169], v[120:121] op_sel_hi:[0,1]
	s_cmp_lt_i32 s39, s53
	v_cvt_pk_bf16_f32 v120, v124, v125
	v_cvt_pk_bf16_f32 v121, v126, v127
	v_cvt_pk_bf16_f32 v122, v122, v123
	v_cvt_pk_bf16_f32 v123, v174, v175
	s_cselect_b64 vcc, -1, 0
	global_store_dwordx4 v[172:173], v[120:123], off sc1
	v_pk_fma_f32 v[118:119], v[118:119], v[170:171], v[134:135] op_sel_hi:[1,0,1]
	v_pk_fma_f32 v[116:117], v[116:117], v[170:171], v[132:133] op_sel_hi:[1,0,1]
	v_cndmask_b32_e32 v120, 1.0, v165, vcc
	v_pk_fma_f32 v[114:115], v[114:115], v[170:171], v[130:131] op_sel_hi:[1,0,1]
	v_pk_fma_f32 v[112:113], v[112:113], v[170:171], v[128:129] op_sel_hi:[1,0,1]
	v_pk_mul_f32 v[118:119], v[120:121], v[118:119] op_sel_hi:[0,1]
	v_pk_mul_f32 v[116:117], v[120:121], v[116:117] op_sel_hi:[0,1]
	v_pk_mul_f32 v[122:123], v[120:121], v[114:115] op_sel_hi:[0,1]
	v_pk_mul_f32 v[114:115], v[120:121], v[112:113] op_sel_hi:[0,1]
	s_lshl_b64 s[22:23], 1, s22
	v_cvt_pk_bf16_f32 v112, v116, v117
	v_cvt_pk_bf16_f32 v113, v118, v119
	v_cvt_pk_bf16_f32 v114, v114, v115
	v_cvt_pk_bf16_f32 v115, v122, v123
	v_lshl_add_u64 v[116:117], s[22:23], 1, v[172:173]
	global_store_dwordx4 v[116:117], v[112:115], off sc1
	ds_read_b32 v112, v163 offset:64
	s_andn2_b64 vcc, exec, s[12:13]
	v_cndmask_b32_e64 v114, 0, 1, s[12:13]
	v_or_b32_e32 v113, 16, v162
	v_cmp_ne_u32_e64 s[38:39], 1, v114
	s_mov_b64 s[12:13], -1
	s_cbranch_vccnz .LBB0_585
	v_mad_i64_i32 v[114:115], s[12:13], s63, v113, 0
	v_lshl_add_u64 v[114:115], v[114:115], 1, s[18:19]
	v_lshl_add_u64 v[114:115], v[166:167], 1, v[114:115]
	s_mov_b64 s[12:13], 0

.LBB0_587:
	v_mov_b32_e32 v169, v168
	s_waitcnt lgkmcnt(0)
	v_pk_fma_f32 v[110:111], v[110:111], v[112:113], v[142:143] op_sel_hi:[1,0,1]
	v_pk_fma_f32 v[108:109], v[108:109], v[112:113], v[140:141] op_sel_hi:[1,0,1]
	v_mov_b32_e32 v116, v168
	v_mov_b32_e32 v117, v168
	v_pk_fma_f32 v[106:107], v[106:107], v[112:113], v[138:139] op_sel_hi:[1,0,1]
	v_pk_fma_f32 v[104:105], v[104:105], v[112:113], v[136:137] op_sel_hi:[1,0,1]
	v_pk_mul_f32 v[110:111], v[116:117], v[110:111]
	v_pk_mul_f32 v[108:109], v[168:169], v[108:109]
	v_pk_mul_f32 v[116:117], v[116:117], v[106:107]
	v_pk_mul_f32 v[106:107], v[168:169], v[104:105]
	v_mov_b32_e32 v121, v120
	v_cvt_pk_bf16_f32 v104, v108, v109
	v_cvt_pk_bf16_f32 v105, v110, v111
	v_cvt_pk_bf16_f32 v106, v106, v107
	v_cvt_pk_bf16_f32 v107, v116, v117
	v_pk_fma_f32 v[100:101], v[100:101], v[112:113], v[132:133] op_sel_hi:[1,0,1]
	v_pk_fma_f32 v[96:97], v[96:97], v[112:113], v[128:129] op_sel_hi:[1,0,1]
	global_store_dwordx4 v[114:115], v[104:107], off sc1
	v_pk_fma_f32 v[102:103], v[102:103], v[112:113], v[134:135] op_sel_hi:[1,0,1]
	v_pk_mul_f32 v[100:101], v[120:121], v[100:101]
	v_mov_b32_e32 v104, v120
	v_mov_b32_e32 v105, v120
	v_pk_fma_f32 v[98:99], v[98:99], v[112:113], v[130:131] op_sel_hi:[1,0,1]
	v_pk_mul_f32 v[96:97], v[120:121], v[96:97]
	v_pk_mul_f32 v[102:103], v[104:105], v[102:103]
	v_pk_mul_f32 v[104:105], v[104:105], v[98:99]
	v_cvt_pk_bf16_f32 v98, v100, v101
	v_cvt_pk_bf16_f32 v100, v96, v97
	ds_read_b32 v96, v163 offset:128
	s_lshl_b64 s[12:13], 1, s12
	v_cvt_pk_bf16_f32 v99, v102, v103
	v_cvt_pk_bf16_f32 v101, v104, v105
	v_lshl_add_u64 v[102:103], s[12:13], 1, v[114:115]
	v_or_b32_e32 v97, 32, v162
	s_and_b64 vcc, exec, s[38:39]
	s_mov_b64 s[12:13], -1
	global_store_dwordx4 v[102:103], v[98:101], off sc1
	s_cbranch_vccnz .LBB0_589
	s_nop 0
	v_mad_i64_i32 v[98:99], s[12:13], s63, v97, 0
	v_lshl_add_u64 v[98:99], v[98:99], 1, s[18:19]
	v_lshl_add_u64 v[98:99], v[166:167], 1, v[98:99]
	s_mov_b64 s[12:13], 0

.LBB0_591:
	s_waitcnt lgkmcnt(0)
	v_pk_fma_f32 v[94:95], v[94:95], v[96:97], v[142:143] op_sel_hi:[1,0,1]
	v_pk_fma_f32 v[92:93], v[92:93], v[96:97], v[140:141] op_sel_hi:[1,0,1]
	v_mov_b32_e32 v100, v168
	v_mov_b32_e32 v101, v168
	v_pk_fma_f32 v[90:91], v[90:91], v[96:97], v[138:139] op_sel_hi:[1,0,1]
	v_pk_fma_f32 v[88:89], v[88:89], v[96:97], v[136:137] op_sel_hi:[1,0,1]
	v_pk_mul_f32 v[94:95], v[100:101], v[94:95]
	v_pk_mul_f32 v[92:93], v[168:169], v[92:93]
	v_pk_mul_f32 v[100:101], v[100:101], v[90:91]
	v_pk_mul_f32 v[90:91], v[168:169], v[88:89]
	v_cvt_pk_bf16_f32 v88, v92, v93
	v_cvt_pk_bf16_f32 v89, v94, v95
	v_cvt_pk_bf16_f32 v90, v90, v91
	v_cvt_pk_bf16_f32 v91, v100, v101
	v_pk_fma_f32 v[84:85], v[84:85], v[96:97], v[132:133] op_sel_hi:[1,0,1]
	v_pk_fma_f32 v[80:81], v[80:81], v[96:97], v[128:129] op_sel_hi:[1,0,1]
	global_store_dwordx4 v[98:99], v[88:91], off sc1
	v_pk_fma_f32 v[86:87], v[86:87], v[96:97], v[134:135] op_sel_hi:[1,0,1]
	v_pk_mul_f32 v[84:85], v[120:121], v[84:85]
	v_mov_b32_e32 v88, v120
	v_mov_b32_e32 v89, v120
	v_pk_fma_f32 v[82:83], v[82:83], v[96:97], v[130:131] op_sel_hi:[1,0,1]
	v_pk_mul_f32 v[80:81], v[120:121], v[80:81]
	v_pk_mul_f32 v[86:87], v[88:89], v[86:87]
	v_pk_mul_f32 v[88:89], v[88:89], v[82:83]
	v_cvt_pk_bf16_f32 v82, v84, v85
	v_cvt_pk_bf16_f32 v84, v80, v81
	ds_read_b32 v80, v163 offset:192
	s_lshl_b64 s[12:13], 1, s12
	v_cvt_pk_bf16_f32 v83, v86, v87
	v_cvt_pk_bf16_f32 v85, v88, v89
	v_lshl_add_u64 v[86:87], s[12:13], 1, v[98:99]
	v_or_b32_e32 v81, 48, v162
	s_and_b64 vcc, exec, s[38:39]
	s_mov_b64 s[12:13], -1
	global_store_dwordx4 v[86:87], v[82:85], off sc1
	s_cbranch_vccnz .LBB0_593
	s_nop 0
	v_mad_i64_i32 v[82:83], s[12:13], s63, v81, 0
	v_lshl_add_u64 v[82:83], v[82:83], 1, s[18:19]
	v_lshl_add_u64 v[82:83], v[166:167], 1, v[82:83]
	s_mov_b64 s[12:13], 0

.LBB0_595:
	s_waitcnt lgkmcnt(0)
	v_pk_fma_f32 v[78:79], v[78:79], v[80:81], v[142:143] op_sel_hi:[1,0,1]
	v_pk_fma_f32 v[76:77], v[76:77], v[80:81], v[140:141] op_sel_hi:[1,0,1]
	v_mov_b32_e32 v84, v168
	v_mov_b32_e32 v85, v168
	v_pk_fma_f32 v[74:75], v[74:75], v[80:81], v[138:139] op_sel_hi:[1,0,1]
	v_pk_fma_f32 v[72:73], v[72:73], v[80:81], v[136:137] op_sel_hi:[1,0,1]
	v_pk_mul_f32 v[78:79], v[84:85], v[78:79]
	v_pk_mul_f32 v[76:77], v[168:169], v[76:77]
	v_pk_mul_f32 v[84:85], v[84:85], v[74:75]
	v_pk_mul_f32 v[74:75], v[168:169], v[72:73]
	v_cvt_pk_bf16_f32 v72, v76, v77
	v_cvt_pk_bf16_f32 v73, v78, v79
	v_cvt_pk_bf16_f32 v74, v74, v75
	v_cvt_pk_bf16_f32 v75, v84, v85
	v_pk_fma_f32 v[68:69], v[68:69], v[80:81], v[132:133] op_sel_hi:[1,0,1]
	v_pk_fma_f32 v[64:65], v[64:65], v[80:81], v[128:129] op_sel_hi:[1,0,1]
	global_store_dwordx4 v[82:83], v[72:75], off sc1
	v_pk_fma_f32 v[70:71], v[70:71], v[80:81], v[134:135] op_sel_hi:[1,0,1]
	v_pk_mul_f32 v[68:69], v[120:121], v[68:69]
	v_mov_b32_e32 v72, v120
	v_mov_b32_e32 v73, v120
	v_pk_fma_f32 v[66:67], v[66:67], v[80:81], v[130:131] op_sel_hi:[1,0,1]
	v_pk_mul_f32 v[64:65], v[120:121], v[64:65]
	v_pk_mul_f32 v[70:71], v[72:73], v[70:71]
	v_pk_mul_f32 v[72:73], v[72:73], v[66:67]
	v_cvt_pk_bf16_f32 v66, v68, v69
	v_cvt_pk_bf16_f32 v68, v64, v65
	ds_read_b32 v64, v163 offset:512
	s_lshl_b64 s[12:13], 1, s12
	v_cvt_pk_bf16_f32 v67, v70, v71
	v_cvt_pk_bf16_f32 v69, v72, v73
	v_lshl_add_u64 v[70:71], s[12:13], 1, v[82:83]
	v_add_u32_e32 v65, 0x80, v162
	s_and_b64 vcc, exec, s[38:39]
	s_mov_b64 s[12:13], -1
	global_store_dwordx4 v[70:71], v[66:69], off sc1
	s_cbranch_vccnz .LBB0_597
	s_nop 0
	v_mad_i64_i32 v[66:67], s[12:13], s63, v65, 0
	v_lshl_add_u64 v[66:67], v[66:67], 1, s[18:19]
	v_lshl_add_u64 v[66:67], v[166:167], 1, v[66:67]
	s_mov_b64 s[12:13], 0

.LBB0_599:
	s_waitcnt lgkmcnt(0)
	v_pk_fma_f32 v[62:63], v[62:63], v[64:65], v[142:143] op_sel_hi:[1,0,1]
	v_pk_fma_f32 v[60:61], v[60:61], v[64:65], v[140:141] op_sel_hi:[1,0,1]
	v_mov_b32_e32 v68, v168
	v_mov_b32_e32 v69, v168
	v_pk_fma_f32 v[58:59], v[58:59], v[64:65], v[138:139] op_sel_hi:[1,0,1]
	v_pk_fma_f32 v[56:57], v[56:57], v[64:65], v[136:137] op_sel_hi:[1,0,1]
	v_pk_mul_f32 v[62:63], v[68:69], v[62:63]
	v_pk_mul_f32 v[60:61], v[168:169], v[60:61]
	v_pk_mul_f32 v[68:69], v[68:69], v[58:59]
	v_pk_mul_f32 v[58:59], v[168:169], v[56:57]
	v_cvt_pk_bf16_f32 v56, v60, v61
	v_cvt_pk_bf16_f32 v57, v62, v63
	v_cvt_pk_bf16_f32 v58, v58, v59
	v_cvt_pk_bf16_f32 v59, v68, v69
	v_pk_fma_f32 v[52:53], v[52:53], v[64:65], v[132:133] op_sel_hi:[1,0,1]
	v_pk_fma_f32 v[48:49], v[48:49], v[64:65], v[128:129] op_sel_hi:[1,0,1]
	global_store_dwordx4 v[66:67], v[56:59], off sc1
	v_pk_fma_f32 v[54:55], v[54:55], v[64:65], v[134:135] op_sel_hi:[1,0,1]
	v_pk_mul_f32 v[52:53], v[120:121], v[52:53]
	v_mov_b32_e32 v56, v120
	v_mov_b32_e32 v57, v120
	v_pk_fma_f32 v[50:51], v[50:51], v[64:65], v[130:131] op_sel_hi:[1,0,1]
	v_pk_mul_f32 v[48:49], v[120:121], v[48:49]
	v_pk_mul_f32 v[54:55], v[56:57], v[54:55]
	v_pk_mul_f32 v[56:57], v[56:57], v[50:51]
	v_cvt_pk_bf16_f32 v50, v52, v53
	v_cvt_pk_bf16_f32 v52, v48, v49
	ds_read_b32 v48, v163 offset:576
	s_lshl_b64 s[12:13], 1, s12
	v_cvt_pk_bf16_f32 v51, v54, v55
	v_cvt_pk_bf16_f32 v53, v56, v57
	v_lshl_add_u64 v[54:55], s[12:13], 1, v[66:67]
	v_add_u32_e32 v49, 0x90, v162
	s_and_b64 vcc, exec, s[38:39]
	s_mov_b64 s[12:13], -1
	global_store_dwordx4 v[54:55], v[50:53], off sc1
	s_cbranch_vccnz .LBB0_601
	s_nop 0
	v_mad_i64_i32 v[50:51], s[12:13], s63, v49, 0
	v_lshl_add_u64 v[50:51], v[50:51], 1, s[18:19]
	v_lshl_add_u64 v[50:51], v[166:167], 1, v[50:51]
	s_mov_b64 s[12:13], 0

.LBB0_603:
	s_waitcnt lgkmcnt(0)
	v_pk_fma_f32 v[46:47], v[46:47], v[48:49], v[142:143] op_sel_hi:[1,0,1]
	v_pk_fma_f32 v[44:45], v[44:45], v[48:49], v[140:141] op_sel_hi:[1,0,1]
	v_mov_b32_e32 v52, v168
	v_mov_b32_e32 v53, v168
	v_pk_fma_f32 v[42:43], v[42:43], v[48:49], v[138:139] op_sel_hi:[1,0,1]
	v_pk_fma_f32 v[40:41], v[40:41], v[48:49], v[136:137] op_sel_hi:[1,0,1]
	v_pk_mul_f32 v[46:47], v[52:53], v[46:47]
	v_pk_mul_f32 v[44:45], v[168:169], v[44:45]
	v_pk_mul_f32 v[52:53], v[52:53], v[42:43]
	v_pk_mul_f32 v[42:43], v[168:169], v[40:41]
	v_cvt_pk_bf16_f32 v40, v44, v45
	v_cvt_pk_bf16_f32 v41, v46, v47
	v_cvt_pk_bf16_f32 v42, v42, v43
	v_cvt_pk_bf16_f32 v43, v52, v53
	v_pk_fma_f32 v[36:37], v[36:37], v[48:49], v[132:133] op_sel_hi:[1,0,1]
	v_pk_fma_f32 v[32:33], v[32:33], v[48:49], v[128:129] op_sel_hi:[1,0,1]
	global_store_dwordx4 v[50:51], v[40:43], off sc1
	v_pk_fma_f32 v[38:39], v[38:39], v[48:49], v[134:135] op_sel_hi:[1,0,1]
	v_pk_mul_f32 v[36:37], v[120:121], v[36:37]
	v_mov_b32_e32 v40, v120
	v_mov_b32_e32 v41, v120
	v_pk_fma_f32 v[34:35], v[34:35], v[48:49], v[130:131] op_sel_hi:[1,0,1]
	v_pk_mul_f32 v[32:33], v[120:121], v[32:33]
	v_pk_mul_f32 v[38:39], v[40:41], v[38:39]
	v_pk_mul_f32 v[40:41], v[40:41], v[34:35]
	v_cvt_pk_bf16_f32 v34, v36, v37
	v_cvt_pk_bf16_f32 v36, v32, v33
	ds_read_b32 v32, v163 offset:640
	s_lshl_b64 s[12:13], 1, s12
	v_cvt_pk_bf16_f32 v35, v38, v39
	v_cvt_pk_bf16_f32 v37, v40, v41
	v_lshl_add_u64 v[38:39], s[12:13], 1, v[50:51]
	v_add_u32_e32 v33, 0xa0, v162
	s_and_b64 vcc, exec, s[38:39]
	s_mov_b64 s[12:13], -1
	global_store_dwordx4 v[38:39], v[34:37], off sc1
	s_cbranch_vccnz .LBB0_605
	s_nop 0
	v_mad_i64_i32 v[34:35], s[12:13], s63, v33, 0
	v_lshl_add_u64 v[34:35], v[34:35], 1, s[18:19]
	v_lshl_add_u64 v[34:35], v[166:167], 1, v[34:35]
	s_mov_b64 s[12:13], 0

.LBB0_607:
	s_waitcnt lgkmcnt(0)
	v_pk_fma_f32 v[30:31], v[30:31], v[32:33], v[142:143] op_sel_hi:[1,0,1]
	v_pk_fma_f32 v[28:29], v[28:29], v[32:33], v[140:141] op_sel_hi:[1,0,1]
	v_mov_b32_e32 v36, v168
	v_mov_b32_e32 v37, v168
	v_pk_fma_f32 v[26:27], v[26:27], v[32:33], v[138:139] op_sel_hi:[1,0,1]
	v_pk_fma_f32 v[24:25], v[24:25], v[32:33], v[136:137] op_sel_hi:[1,0,1]
	v_pk_mul_f32 v[30:31], v[36:37], v[30:31]
	v_pk_mul_f32 v[28:29], v[168:169], v[28:29]
	v_pk_mul_f32 v[36:37], v[36:37], v[26:27]
	v_pk_mul_f32 v[26:27], v[168:169], v[24:25]
	v_cvt_pk_bf16_f32 v24, v28, v29
	v_cvt_pk_bf16_f32 v25, v30, v31
	v_cvt_pk_bf16_f32 v26, v26, v27
	v_cvt_pk_bf16_f32 v27, v36, v37
	v_pk_fma_f32 v[20:21], v[20:21], v[32:33], v[132:133] op_sel_hi:[1,0,1]
	v_pk_fma_f32 v[16:17], v[16:17], v[32:33], v[128:129] op_sel_hi:[1,0,1]
	global_store_dwordx4 v[34:35], v[24:27], off sc1
	v_pk_fma_f32 v[22:23], v[22:23], v[32:33], v[134:135] op_sel_hi:[1,0,1]
	v_pk_mul_f32 v[20:21], v[120:121], v[20:21]
	v_mov_b32_e32 v24, v120
	v_mov_b32_e32 v25, v120
	v_pk_fma_f32 v[18:19], v[18:19], v[32:33], v[130:131] op_sel_hi:[1,0,1]
	v_pk_mul_f32 v[16:17], v[120:121], v[16:17]
	v_pk_mul_f32 v[22:23], v[24:25], v[22:23]
	v_pk_mul_f32 v[24:25], v[24:25], v[18:19]
	v_cvt_pk_bf16_f32 v18, v20, v21
	v_cvt_pk_bf16_f32 v20, v16, v17
	ds_read_b32 v16, v163 offset:704
	s_lshl_b64 s[12:13], 1, s12
	v_cvt_pk_bf16_f32 v19, v22, v23
	v_cvt_pk_bf16_f32 v21, v24, v25
	v_lshl_add_u64 v[22:23], s[12:13], 1, v[34:35]
	v_add_u32_e32 v17, 0xb0, v162
	s_and_b64 vcc, exec, s[38:39]
	s_mov_b64 s[12:13], -1
	global_store_dwordx4 v[22:23], v[18:21], off sc1
	s_cbranch_vccnz .LBB0_609
	s_nop 0
	v_mad_i64_i32 v[18:19], s[12:13], s63, v17, 0
	v_lshl_add_u64 v[18:19], v[18:19], 1, s[18:19]
	v_lshl_add_u64 v[18:19], v[166:167], 1, v[18:19]
	s_mov_b64 s[12:13], 0

.LBB0_611:
	s_waitcnt lgkmcnt(0)
	v_pk_fma_f32 v[14:15], v[14:15], v[16:17], v[142:143] op_sel_hi:[1,0,1]
	v_pk_fma_f32 v[12:13], v[12:13], v[16:17], v[140:141] op_sel_hi:[1,0,1]
	v_mov_b32_e32 v20, v168
	v_mov_b32_e32 v21, v168
	v_pk_fma_f32 v[10:11], v[10:11], v[16:17], v[138:139] op_sel_hi:[1,0,1]
	v_pk_fma_f32 v[8:9], v[8:9], v[16:17], v[136:137] op_sel_hi:[1,0,1]
	v_pk_mul_f32 v[14:15], v[20:21], v[14:15]
	v_pk_mul_f32 v[12:13], v[168:169], v[12:13]
	v_pk_mul_f32 v[20:21], v[20:21], v[10:11]
	v_pk_mul_f32 v[10:11], v[168:169], v[8:9]
	v_cvt_pk_bf16_f32 v8, v12, v13
	v_cvt_pk_bf16_f32 v9, v14, v15
	v_cvt_pk_bf16_f32 v10, v10, v11
	v_cvt_pk_bf16_f32 v11, v20, v21
	global_store_dwordx4 v[18:19], v[8:11], off sc1
	v_pk_fma_f32 v[6:7], v[6:7], v[16:17], v[134:135] op_sel_hi:[1,0,1]
	v_pk_fma_f32 v[4:5], v[4:5], v[16:17], v[132:133] op_sel_hi:[1,0,1]
	v_mov_b32_e32 v8, v120
	v_mov_b32_e32 v9, v120
	v_pk_fma_f32 v[2:3], v[2:3], v[16:17], v[130:131] op_sel_hi:[1,0,1]
	v_pk_fma_f32 v[0:1], v[0:1], v[16:17], v[128:129] op_sel_hi:[1,0,1]
	v_pk_mul_f32 v[6:7], v[8:9], v[6:7]
	v_pk_mul_f32 v[4:5], v[120:121], v[4:5]
	v_pk_mul_f32 v[8:9], v[8:9], v[2:3]
	v_pk_mul_f32 v[2:3], v[120:121], v[0:1]
	s_lshl_b64 s[12:13], 1, s12
	v_cvt_pk_bf16_f32 v0, v4, v5
	v_cvt_pk_bf16_f32 v1, v6, v7
	v_cvt_pk_bf16_f32 v2, v2, v3
	v_cvt_pk_bf16_f32 v3, v8, v9
	v_lshl_add_u64 v[4:5], s[12:13], 1, v[18:19]
	global_store_dwordx4 v[4:5], v[0:3], off sc1
	s_andn2_b64 vcc, exec, s[42:43]
	s_mov_b64 s[12:13], -1
	s_cbranch_vccnz .LBB0_495
